# GLA forget-gate dot products via packed f32 FMA with LDS rows prefetched; ex_chunk loads no longer wait for GEMM epilogue stores
# speedup vs baseline: 1.0140x; 1.0025x over previous
.LBB0_468:
	v_mov_b32_e32 v38, v0
	v_readlane_b32 s0, v250, 43
	v_ashrrev_i32_e32 v129, 3, v38
	v_add_u32_e32 v6, s88, v129
	s_waitcnt lgkmcnt(0)
	v_ashrrev_i32_e32 v7, 31, v6
	v_lshlrev_b64 v[6:7], 7, v[6:7]
	v_readlane_b32 s1, v250, 44
	v_lshlrev_b32_e32 v1, 3, v38
	v_and_b32_e32 v138, 56, v1
	v_lshl_add_u64 v[6:7], s[0:1], 0, v[6:7]
	v_lshl_add_u64 v[6:7], v[6:7], 0, v[138:139]
	v_lshlrev_b32_sdwa v40, v230, v38 dst_sel:DWORD dst_unused:UNUSED_PAD src0_sel:DWORD src1_sel:BYTE_0
	v_mov_b32_e32 v41, v139
	v_readlane_b32 s0, v254, 41
	global_load_dwordx2 v[42:43], v[6:7], off
	v_lshl_add_u64 v[6:7], s[60:61], 0, v[40:41]
	v_readlane_b32 s1, v254, 42
	v_ashrrev_i32_e32 v121, 8, v38
	s_movk_i32 s4, 0x2800
	v_lshl_add_u64 v[8:9], v[6:7], 0, s[0:1]
	v_readlane_b32 s0, v254, 12
	v_readlane_b32 s1, v254, 13
	global_load_dword v99, v[8:9], off
	v_lshl_add_u32 v39, v121, 5, s88
	v_lshl_add_u64 v[8:9], v[6:7], 0, s[0:1]
	v_readlane_b32 s0, v254, 14
	v_readlane_b32 s1, v254, 15
	global_load_dword v100, v[8:9], off
	v_lshlrev_b32_sdwa v84, v227, v38 dst_sel:DWORD dst_unused:UNUSED_PAD src0_sel:DWORD src1_sel:BYTE_0
	v_lshl_add_u64 v[8:9], v[6:7], 0, s[0:1]
	v_readlane_b32 s0, v253, 56
	v_readlane_b32 s1, v253, 57
	global_load_dword v101, v[8:9], off
	v_mov_b32_e32 v85, v139
	v_lshl_add_u64 v[8:9], v[6:7], 0, s[0:1]
	v_readlane_b32 s0, v254, 16
	v_readlane_b32 s1, v254, 17
	global_load_dword v104, v[8:9], off
	v_or_b32_e32 v41, 1, v39
	v_lshl_add_u64 v[8:9], v[6:7], 0, s[0:1]
	v_readlane_b32 s0, v254, 18
	v_readlane_b32 s1, v254, 19
	global_load_dword v105, v[8:9], off
	v_ashrrev_i32_e32 v130, 6, v38
	v_lshl_add_u64 v[8:9], v[6:7], 0, s[0:1]
	v_readlane_b32 s0, v254, 20
	v_readlane_b32 s1, v254, 21
	global_load_dword v106, v[8:9], off
	v_add_u32_e32 v10, 0x200, v38
	v_lshl_add_u64 v[8:9], v[6:7], 0, s[0:1]
	v_readlane_b32 s0, v254, 22
	v_readlane_b32 s1, v254, 23
	global_load_dword v107, v[8:9], off
	v_mov_b32_e32 v45, v139
	v_lshl_add_u64 v[8:9], v[6:7], 0, s[0:1]
	v_readlane_b32 s0, v254, 45
	v_readlane_b32 s1, v254, 46
	global_load_dword v109, v[8:9], off
	v_ashrrev_i32_e32 v131, 6, v10
	v_lshl_add_u64 v[8:9], v[6:7], 0, s[0:1]
	v_readlane_b32 s0, v254, 24
	v_readlane_b32 s1, v254, 25
	global_load_dword v108, v[8:9], off
	v_add_u32_e32 v10, s88, v131
	v_lshl_add_u64 v[8:9], v[6:7], 0, s[0:1]
	v_readlane_b32 s0, v254, 26
	v_readlane_b32 s1, v254, 27
	global_load_dword v112, v[8:9], off
	v_add_u32_e32 v14, 0x400, v38
	v_lshl_add_u64 v[8:9], v[6:7], 0, s[0:1]
	v_readlane_b32 s0, v254, 28
	v_readlane_b32 s1, v254, 29
	global_load_dword v113, v[8:9], off
	v_ashrrev_i32_e32 v132, 6, v14
	v_lshl_add_u64 v[8:9], v[6:7], 0, s[0:1]
	v_readlane_b32 s0, v254, 30
	v_readlane_b32 s1, v254, 31
	global_load_dword v114, v[8:9], off
	v_add_u32_e32 v14, s88, v132
	v_lshl_add_u64 v[8:9], v[6:7], 0, s[0:1]
	v_readlane_b32 s0, v254, 32
	v_readlane_b32 s1, v254, 33
	global_load_dword v115, v[8:9], off
	v_add_u32_e32 v18, 0x600, v38
	v_lshl_add_u64 v[8:9], v[6:7], 0, s[0:1]
	v_readlane_b32 s0, v254, 34
	v_readlane_b32 s1, v254, 35
	global_load_dword v116, v[8:9], off
	v_ashrrev_i32_e32 v133, 6, v18
	v_lshl_add_u64 v[8:9], v[6:7], 0, s[0:1]
	v_readlane_b32 s0, v254, 36
	v_readlane_b32 s1, v254, 37
	global_load_dword v117, v[8:9], off
	v_add_u32_e32 v18, s88, v133
	v_lshl_add_u64 v[6:7], v[6:7], 0, s[0:1]
	v_readlane_b32 s0, v254, 38
	global_load_dword v120, v[6:7], off
	v_lshlrev_b32_e32 v8, 4, v38
	v_or_b32_sdwa v6, v38, s0 dst_sel:DWORD dst_unused:UNUSED_PAD src0_sel:BYTE_0 src1_sel:DWORD
	v_readlane_b32 s0, v251, 55
	v_readlane_b32 s1, v251, 56
	v_ashrrev_i32_e32 v7, 31, v6
	v_lshl_add_u64 v[6:7], v[6:7], 2, s[62:63]
	v_mov_b64_e32 v[46:47], s[0:1]
	v_mad_i64_i32 v[48:49], s[0:1], v39, s4, v[46:47]
	v_lshl_add_u64 v[86:87], v[48:49], 0, v[84:85]
	v_mad_i64_i32 v[48:49], s[0:1], v41, s4, v[46:47]
	v_or_b32_e32 v41, 2, v39
	v_lshl_add_u64 v[88:89], v[48:49], 0, v[84:85]
	v_mad_i64_i32 v[48:49], s[0:1], v41, s4, v[46:47]
	v_or_b32_e32 v41, 3, v39
	v_lshl_add_u64 v[90:91], v[48:49], 0, v[84:85]
	v_mad_i64_i32 v[48:49], s[0:1], v41, s4, v[46:47]
	v_or_b32_e32 v41, 4, v39
	v_lshl_add_u64 v[92:93], v[48:49], 0, v[84:85]
	v_mad_i64_i32 v[48:49], s[0:1], v41, s4, v[46:47]
	v_or_b32_e32 v41, 5, v39
	v_lshl_add_u64 v[94:95], v[48:49], 0, v[84:85]
	v_mad_i64_i32 v[48:49], s[0:1], v41, s4, v[46:47]
	v_or_b32_e32 v41, 6, v39
	v_lshl_add_u64 v[96:97], v[48:49], 0, v[84:85]
	v_mad_i64_i32 v[48:49], s[0:1], v41, s4, v[46:47]
	v_or_b32_e32 v41, 7, v39
	global_load_dword v122, v[6:7], off
	v_add_u32_e32 v6, s88, v130
	v_lshl_add_u64 v[140:141], v[48:49], 0, v[84:85]
	v_mad_i64_i32 v[48:49], s[0:1], v41, s4, v[46:47]
	v_or_b32_e32 v41, 8, v39
	v_mad_i64_i32 v[6:7], s[0:1], v6, s4, v[46:47]
	v_and_b32_e32 v44, 0x3f0, v8
	v_lshl_add_u64 v[142:143], v[48:49], 0, v[84:85]
	v_mad_i64_i32 v[48:49], s[0:1], v41, s4, v[46:47]
	v_or_b32_e32 v41, 9, v39
	v_lshl_add_u64 v[6:7], v[6:7], 0, v[44:45]
	v_lshl_add_u64 v[146:147], v[48:49], 0, v[84:85]
	v_mad_i64_i32 v[48:49], s[0:1], v41, s4, v[46:47]
	v_or_b32_e32 v41, 10, v39
	v_add_co_u32_e32 v6, vcc, s12, v6
	v_mad_i64_i32 v[10:11], s[0:1], v10, s4, v[46:47]
	v_lshl_add_u64 v[148:149], v[48:49], 0, v[84:85]
	v_mad_i64_i32 v[48:49], s[0:1], v41, s4, v[46:47]
	v_or_b32_e32 v41, 11, v39
	v_addc_co_u32_e32 v7, vcc, 0, v7, vcc
	v_lshl_add_u64 v[10:11], v[10:11], 0, v[44:45]
	v_lshl_add_u64 v[150:151], v[48:49], 0, v[84:85]
	v_mad_i64_i32 v[48:49], s[0:1], v41, s4, v[46:47]
	v_or_b32_e32 v41, 12, v39
	v_add_co_u32_e32 v10, vcc, s12, v10
	v_mad_i64_i32 v[14:15], s[0:1], v14, s4, v[46:47]
	v_lshl_add_u64 v[152:153], v[48:49], 0, v[84:85]
	v_mad_i64_i32 v[48:49], s[0:1], v41, s4, v[46:47]
	v_or_b32_e32 v41, 13, v39
	v_addc_co_u32_e32 v11, vcc, 0, v11, vcc
	v_lshl_add_u64 v[14:15], v[14:15], 0, v[44:45]
	v_add_u32_e32 v22, 0x800, v38
	v_lshl_add_u64 v[154:155], v[48:49], 0, v[84:85]
	v_mad_i64_i32 v[48:49], s[0:1], v41, s4, v[46:47]
	v_or_b32_e32 v41, 14, v39
	v_add_co_u32_e32 v14, vcc, s12, v14
	v_mad_i64_i32 v[18:19], s[0:1], v18, s4, v[46:47]
	v_ashrrev_i32_e32 v134, 6, v22
	v_lshl_add_u64 v[82:83], v[48:49], 0, v[84:85]
	v_mad_i64_i32 v[48:49], s[0:1], v41, s4, v[46:47]
	v_or_b32_e32 v41, 15, v39
	v_addc_co_u32_e32 v15, vcc, 0, v15, vcc
	v_lshl_add_u64 v[18:19], v[18:19], 0, v[44:45]
	v_add_u32_e32 v22, s88, v134
	v_add_u32_e32 v26, 0xa00, v38
	v_lshl_add_u64 v[80:81], v[48:49], 0, v[84:85]
	v_mad_i64_i32 v[48:49], s[0:1], v41, s4, v[46:47]
	v_or_b32_e32 v41, 16, v39
	v_add_co_u32_e32 v18, vcc, s12, v18
	v_mad_i64_i32 v[22:23], s[0:1], v22, s4, v[46:47]
	v_ashrrev_i32_e32 v135, 6, v26
	v_lshl_add_u64 v[78:79], v[48:49], 0, v[84:85]
	v_mad_i64_i32 v[48:49], s[0:1], v41, s4, v[46:47]
	v_or_b32_e32 v41, 17, v39
	v_addc_co_u32_e32 v19, vcc, 0, v19, vcc
	v_lshl_add_u64 v[22:23], v[22:23], 0, v[44:45]
	v_add_u32_e32 v26, s88, v135
	v_add_u32_e32 v30, 0xc00, v38
	v_lshl_add_u64 v[76:77], v[48:49], 0, v[84:85]
	v_mad_i64_i32 v[48:49], s[0:1], v41, s4, v[46:47]
	v_or_b32_e32 v41, 18, v39
	v_add_co_u32_e32 v22, vcc, s12, v22
	v_mad_i64_i32 v[26:27], s[0:1], v26, s4, v[46:47]
	v_ashrrev_i32_e32 v136, 6, v30
	v_lshl_add_u64 v[74:75], v[48:49], 0, v[84:85]
	v_mad_i64_i32 v[48:49], s[0:1], v41, s4, v[46:47]
	v_or_b32_e32 v41, 19, v39
	global_load_dwordx4 v[6:9], v[6:7], off offset:2048
	v_addc_co_u32_e32 v23, vcc, 0, v23, vcc
	v_lshl_add_u64 v[26:27], v[26:27], 0, v[44:45]
	v_add_u32_e32 v30, s88, v136
	v_add_u32_e32 v34, 0xe00, v38
	v_lshl_add_u64 v[72:73], v[48:49], 0, v[84:85]
	v_mad_i64_i32 v[48:49], s[0:1], v41, s4, v[46:47]
	v_or_b32_e32 v41, 20, v39
	global_load_dwordx4 v[10:13], v[10:11], off offset:2048
	v_add_co_u32_e32 v26, vcc, s12, v26
	v_mad_i64_i32 v[30:31], s[0:1], v30, s4, v[46:47]
	v_ashrrev_i32_e32 v137, 6, v34
	v_lshl_add_u64 v[70:71], v[48:49], 0, v[84:85]
	v_mad_i64_i32 v[48:49], s[0:1], v41, s4, v[46:47]
	v_or_b32_e32 v41, 21, v39
	global_load_dwordx4 v[14:17], v[14:15], off offset:2048
	v_addc_co_u32_e32 v27, vcc, 0, v27, vcc
	v_lshl_add_u64 v[30:31], v[30:31], 0, v[44:45]
	v_add_u32_e32 v34, s88, v137
	v_lshl_add_u64 v[68:69], v[48:49], 0, v[84:85]
	v_mad_i64_i32 v[48:49], s[0:1], v41, s4, v[46:47]
	v_or_b32_e32 v41, 22, v39
	global_load_dwordx4 v[18:21], v[18:19], off offset:2048
	v_add_co_u32_e32 v30, vcc, s12, v30
	v_mad_i64_i32 v[34:35], s[0:1], v34, s4, v[46:47]
	v_lshl_add_u64 v[66:67], v[48:49], 0, v[84:85]
	v_mad_i64_i32 v[48:49], s[0:1], v41, s4, v[46:47]
	v_or_b32_e32 v41, 23, v39
	global_load_dwordx4 v[22:25], v[22:23], off offset:2048
	v_addc_co_u32_e32 v31, vcc, 0, v31, vcc
	v_lshl_add_u64 v[34:35], v[34:35], 0, v[44:45]
	v_lshl_add_u64 v[64:65], v[48:49], 0, v[84:85]
	v_mad_i64_i32 v[48:49], s[0:1], v41, s4, v[46:47]
	v_or_b32_e32 v41, 24, v39
	global_load_dwordx4 v[26:29], v[26:27], off offset:2048
	v_add_co_u32_e32 v34, vcc, s12, v34
	v_lshl_add_u64 v[62:63], v[48:49], 0, v[84:85]
	v_mad_i64_i32 v[48:49], s[0:1], v41, s4, v[46:47]
	v_or_b32_e32 v41, 25, v39
	global_load_dwordx4 v[30:33], v[30:31], off offset:2048
	v_addc_co_u32_e32 v35, vcc, 0, v35, vcc
	v_lshl_add_u64 v[60:61], v[48:49], 0, v[84:85]
	v_mad_i64_i32 v[48:49], s[0:1], v41, s4, v[46:47]
	v_or_b32_e32 v41, 26, v39
	global_load_dwordx4 v[34:37], v[34:35], off offset:2048
	v_lshl_add_u64 v[58:59], v[48:49], 0, v[84:85]
	v_mad_i64_i32 v[48:49], s[0:1], v41, s4, v[46:47]
	v_or_b32_e32 v41, 27, v39
	v_lshl_add_u64 v[56:57], v[48:49], 0, v[84:85]
	v_mad_i64_i32 v[48:49], s[0:1], v41, s4, v[46:47]
	v_or_b32_e32 v41, 28, v39
	v_lshl_add_u64 v[54:55], v[48:49], 0, v[84:85]
	v_mad_i64_i32 v[48:49], s[0:1], v41, s4, v[46:47]
	v_or_b32_e32 v41, 29, v39
	v_lshl_add_u64 v[52:53], v[48:49], 0, v[84:85]
	v_mad_i64_i32 v[48:49], s[0:1], v41, s4, v[46:47]
	v_or_b32_e32 v41, 30, v39
	v_or_b32_e32 v39, 31, v39
	v_lshl_add_u64 v[50:51], v[48:49], 0, v[84:85]
	v_mad_i64_i32 v[48:49], s[0:1], v41, s4, v[46:47]
	v_mad_i64_i32 v[46:47], s[0:1], v39, s4, v[46:47]
	v_lshl_add_u64 v[48:49], v[48:49], 0, v[84:85]
	v_lshl_add_u64 v[46:47], v[46:47], 0, v[84:85]
	v_add_co_u32_e32 v84, vcc, s12, v86
	v_readlane_b32 s5, v253, 4
	s_nop 0
	v_addc_co_u32_e32 v85, vcc, 0, v87, vcc
	global_load_ushort v127, v[84:85], off offset:512
	global_load_ushort v128, v[86:87], off offset:2048
	v_add_co_u32_e32 v84, vcc, s12, v88
	v_readlane_b32 s0, v253, 5
	s_nop 0
	v_addc_co_u32_e32 v85, vcc, 0, v89, vcc
	global_load_ushort v125, v[84:85], off offset:512
	global_load_ushort v126, v[88:89], off offset:2048
	v_add_co_u32_e32 v84, vcc, s12, v90
	s_movk_i32 s4, 0x410
	s_nop 0
	v_addc_co_u32_e32 v85, vcc, 0, v91, vcc
	global_load_ushort v123, v[84:85], off offset:512
	global_load_ushort v124, v[90:91], off offset:2048
	v_add_co_u32_e32 v84, vcc, s12, v92
	v_readfirstlane_b32 s20, v38
	s_nop 0
	v_addc_co_u32_e32 v85, vcc, 0, v93, vcc
	global_load_ushort v118, v[84:85], off offset:512
	global_load_ushort v119, v[92:93], off offset:2048
	v_add_co_u32_e32 v84, vcc, s12, v94
	s_nop 1
	v_addc_co_u32_e32 v85, vcc, 0, v95, vcc
	global_load_ushort v110, v[84:85], off offset:512
	global_load_ushort v111, v[94:95], off offset:2048
	v_add_co_u32_e32 v84, vcc, s12, v96
	s_nop 1
	v_addc_co_u32_e32 v85, vcc, 0, v97, vcc
	global_load_ushort v102, v[84:85], off offset:512
	global_load_ushort v103, v[96:97], off offset:2048
	v_add_co_u32_e32 v84, vcc, s12, v140
	s_nop 1
	v_addc_co_u32_e32 v85, vcc, 0, v141, vcc
	global_load_ushort v97, v[84:85], off offset:512
	global_load_ushort v98, v[140:141], off offset:2048
	v_add_co_u32_e32 v84, vcc, s12, v142
	s_nop 1
	v_addc_co_u32_e32 v85, vcc, 0, v143, vcc
	global_load_ushort v95, v[84:85], off offset:512
	global_load_ushort v96, v[142:143], off offset:2048
	v_add_co_u32_e32 v84, vcc, s12, v146
	s_nop 1
	v_addc_co_u32_e32 v85, vcc, 0, v147, vcc
	global_load_ushort v93, v[84:85], off offset:512
	global_load_ushort v94, v[146:147], off offset:2048
	v_add_co_u32_e32 v84, vcc, s12, v148
	s_nop 1
	v_addc_co_u32_e32 v85, vcc, 0, v149, vcc
	global_load_ushort v91, v[84:85], off offset:512
	global_load_ushort v92, v[148:149], off offset:2048
	v_add_co_u32_e32 v84, vcc, s12, v150
	s_nop 1
	v_addc_co_u32_e32 v85, vcc, 0, v151, vcc
	global_load_ushort v89, v[84:85], off offset:512
	global_load_ushort v90, v[150:151], off offset:2048
	v_add_co_u32_e32 v84, vcc, s12, v152
	s_nop 1
	v_addc_co_u32_e32 v85, vcc, 0, v153, vcc
	global_load_ushort v87, v[84:85], off offset:512
	global_load_ushort v88, v[152:153], off offset:2048
	v_add_co_u32_e32 v84, vcc, s12, v154
	s_nop 1
	v_addc_co_u32_e32 v85, vcc, 0, v155, vcc
	v_add_co_u32_e32 v140, vcc, s12, v82
	global_load_ushort v85, v[84:85], off offset:512
	s_nop 0
	global_load_ushort v86, v[154:155], off offset:2048
	v_addc_co_u32_e32 v141, vcc, 0, v83, vcc
	global_load_ushort v84, v[140:141], off offset:512
	s_nop 0
	global_load_ushort v83, v[82:83], off offset:2048
	v_add_co_u32_e32 v140, vcc, s12, v80
	s_nop 1
	v_addc_co_u32_e32 v141, vcc, 0, v81, vcc
	global_load_ushort v82, v[140:141], off offset:512
	s_nop 0
	global_load_ushort v81, v[80:81], off offset:2048
	v_add_co_u32_e32 v140, vcc, s12, v78
	s_nop 1
	v_addc_co_u32_e32 v141, vcc, 0, v79, vcc
	global_load_ushort v80, v[140:141], off offset:512
	s_nop 0
	global_load_ushort v79, v[78:79], off offset:2048
	v_add_co_u32_e32 v140, vcc, s12, v76
	s_nop 1
	v_addc_co_u32_e32 v141, vcc, 0, v77, vcc
	global_load_ushort v78, v[140:141], off offset:512
	s_nop 0
	global_load_ushort v77, v[76:77], off offset:2048
	v_add_co_u32_e32 v140, vcc, s12, v74
	s_nop 1
	v_addc_co_u32_e32 v141, vcc, 0, v75, vcc
	global_load_ushort v76, v[140:141], off offset:512
	s_nop 0
	global_load_ushort v75, v[74:75], off offset:2048
	v_add_co_u32_e32 v140, vcc, s12, v72
	s_nop 1
	v_addc_co_u32_e32 v141, vcc, 0, v73, vcc
	global_load_ushort v74, v[140:141], off offset:512
	s_nop 0
	global_load_ushort v73, v[72:73], off offset:2048
	v_add_co_u32_e32 v140, vcc, s12, v70
	s_nop 1
	v_addc_co_u32_e32 v141, vcc, 0, v71, vcc
	global_load_ushort v72, v[140:141], off offset:512
	s_nop 0
	global_load_ushort v71, v[70:71], off offset:2048
	v_add_co_u32_e32 v140, vcc, s12, v68
	s_nop 1
	v_addc_co_u32_e32 v141, vcc, 0, v69, vcc
	global_load_ushort v70, v[140:141], off offset:512
	s_nop 0
	global_load_ushort v69, v[68:69], off offset:2048
	v_add_co_u32_e32 v140, vcc, s12, v66
	s_nop 1
	v_addc_co_u32_e32 v141, vcc, 0, v67, vcc
	global_load_ushort v68, v[140:141], off offset:512
	s_nop 0
	global_load_ushort v67, v[66:67], off offset:2048
	v_add_co_u32_e32 v140, vcc, s12, v64
	s_nop 1
	v_addc_co_u32_e32 v141, vcc, 0, v65, vcc
	global_load_ushort v66, v[140:141], off offset:512
	s_nop 0
	global_load_ushort v65, v[64:65], off offset:2048
	v_add_co_u32_e32 v140, vcc, s12, v62
	s_nop 1
	v_addc_co_u32_e32 v141, vcc, 0, v63, vcc
	global_load_ushort v64, v[140:141], off offset:512
	s_nop 0
	global_load_ushort v63, v[62:63], off offset:2048
	v_add_co_u32_e32 v140, vcc, s12, v60
	s_nop 1
	v_addc_co_u32_e32 v141, vcc, 0, v61, vcc
	global_load_ushort v62, v[140:141], off offset:512
	s_nop 0
	global_load_ushort v61, v[60:61], off offset:2048
	v_add_co_u32_e32 v140, vcc, s12, v58
	s_nop 1
	v_addc_co_u32_e32 v141, vcc, 0, v59, vcc
	global_load_ushort v60, v[140:141], off offset:512
	s_nop 0
	global_load_ushort v59, v[58:59], off offset:2048
	v_add_co_u32_e32 v140, vcc, s12, v56
	s_nop 1
	v_addc_co_u32_e32 v141, vcc, 0, v57, vcc
	global_load_ushort v58, v[140:141], off offset:512
	s_nop 0
	global_load_ushort v57, v[56:57], off offset:2048
	v_add_co_u32_e32 v140, vcc, s12, v54
	s_nop 1
	v_addc_co_u32_e32 v141, vcc, 0, v55, vcc
	global_load_ushort v56, v[140:141], off offset:512
	s_nop 0
	global_load_ushort v55, v[54:55], off offset:2048
	v_add_co_u32_e32 v140, vcc, s12, v52
	s_nop 1
	v_addc_co_u32_e32 v141, vcc, 0, v53, vcc
	global_load_ushort v54, v[140:141], off offset:512
	s_nop 0
	global_load_ushort v53, v[52:53], off offset:2048
	v_add_co_u32_e32 v140, vcc, s12, v50
	s_nop 1
	v_addc_co_u32_e32 v141, vcc, 0, v51, vcc
	global_load_ushort v52, v[140:141], off offset:512
	s_nop 0
	global_load_ushort v50, v[50:51], off offset:2048
	v_add_co_u32_e32 v140, vcc, s12, v48
	s_nop 1
	v_addc_co_u32_e32 v141, vcc, 0, v49, vcc
	global_load_ushort v45, v[140:141], off offset:512
	s_nop 0
	global_load_ushort v48, v[48:49], off offset:2048
	v_add_co_u32_e32 v140, vcc, s12, v46
	s_nop 1
	v_addc_co_u32_e32 v141, vcc, 0, v47, vcc
	global_load_ushort v39, v[140:141], off offset:512
	global_load_ushort v41, v[46:47], off offset:2048
	v_lshlrev_b32_e32 v46, 6, v129
	v_add3_u32 v46, s5, v46, v138
	s_waitcnt vmcnt(0)
	ds_write_b64 v46, v[42:43]
	v_add_u32_e32 v42, s0, v44
	v_mad_u64_u32 v[46:47], s[0:1], v130, s4, v[42:43]
	ds_write_b128 v46, v[6:9]
	v_mad_u64_u32 v[6:7], s[0:1], v131, s4, v[42:43]
	ds_write_b128 v6, v[10:13]
	v_mad_u64_u32 v[6:7], s[0:1], v132, s4, v[42:43]
	ds_write_b128 v6, v[14:17]
	v_mad_u64_u32 v[6:7], s[0:1], v133, s4, v[42:43]
	ds_write_b128 v6, v[18:21]
	v_mad_u64_u32 v[6:7], s[0:1], v134, s4, v[42:43]
	ds_write_b128 v6, v[22:25]
	v_mad_u64_u32 v[6:7], s[0:1], v135, s4, v[42:43]
	ds_write_b128 v6, v[26:29]
	v_mad_u64_u32 v[6:7], s[0:1], v136, s4, v[42:43]
	ds_write_b128 v6, v[30:33]
	v_mad_u64_u32 v[6:7], s[0:1], v137, s4, v[42:43]
	v_lshl_add_u32 v10, v121, 11, s5
	ds_write_b128 v6, v[34:37]
	s_waitcnt lgkmcnt(0)
	s_barrier
	v_readlane_b32 s0, v253, 6
	ds_read_b128 v[194:197], v10 offset:0
	ds_read_b128 v[198:201], v10 offset:16
	ds_read_b128 v[202:205], v10 offset:32
	ds_read_b128 v[206:209], v10 offset:48
	ds_read_b128 v[210:213], v10 offset:64
	ds_read_b128 v[214:217], v10 offset:80
	ds_read_b128 v[218:221], v10 offset:96
	ds_read_b128 v[236:239], v10 offset:112
	ds_read_b128 v[240:243], v10 offset:128
	ds_read_b128 v[244:247], v10 offset:144
	ds_read_b128 v[150:153], v10 offset:160
	ds_read_b128 v[156:159], v10 offset:176
	v_mov_b32_e32 v130, v99
	v_mov_b32_e32 v131, v100
	v_mov_b32_e32 v132, v101
	v_mov_b32_e32 v133, v104
	v_mov_b32_e32 v134, v105
	v_mov_b32_e32 v135, v106
	v_mov_b32_e32 v136, v107
	v_mov_b32_e32 v137, v109
	v_mov_b32_e32 v140, v108
	v_mov_b32_e32 v141, v112
	v_mov_b32_e32 v142, v113
	v_mov_b32_e32 v143, v114
	v_mov_b32_e32 v146, v115
	v_mov_b32_e32 v147, v116
	v_mov_b32_e32 v148, v117
	v_mov_b32_e32 v149, v120
	s_waitcnt lgkmcnt(4)
	v_pk_mul_f32 v[194:195], v[130:131], v[194:195]
	v_pk_mul_f32 v[210:211], v[130:131], v[210:211]
	v_pk_fma_f32 v[194:195], v[132:133], v[196:197], v[194:195]
	v_pk_fma_f32 v[210:211], v[132:133], v[212:213], v[210:211]
	v_pk_fma_f32 v[194:195], v[134:135], v[198:199], v[194:195]
	v_pk_fma_f32 v[210:211], v[134:135], v[214:215], v[210:211]
	v_pk_fma_f32 v[194:195], v[136:137], v[200:201], v[194:195]
	v_pk_fma_f32 v[210:211], v[136:137], v[216:217], v[210:211]
	v_pk_fma_f32 v[194:195], v[140:141], v[202:203], v[194:195]
	v_pk_fma_f32 v[210:211], v[140:141], v[218:219], v[210:211]
	v_pk_fma_f32 v[194:195], v[142:143], v[204:205], v[194:195]
	v_pk_fma_f32 v[210:211], v[142:143], v[220:221], v[210:211]
	v_pk_fma_f32 v[194:195], v[146:147], v[206:207], v[194:195]
	v_pk_fma_f32 v[210:211], v[146:147], v[236:237], v[210:211]
	v_pk_fma_f32 v[194:195], v[148:149], v[208:209], v[194:195]
	v_pk_fma_f32 v[210:211], v[148:149], v[238:239], v[210:211]
	v_add_f32_e32 v49, v194, v195
	v_add_f32_e32 v138, v210, v211
	v_add_f32_e32 v49, v122, v49
	v_add_f32_e32 v138, v122, v138
	v_max_f32_e64 v51, -v49, 0
	v_max_f32_e64 v161, -v138, 0
	v_mul_f32_e64 v129, |v49|, s13
	v_mul_f32_e64 v188, |v138|, s13
	v_exp_f32_e32 v129, v129
	v_exp_f32_e32 v188, v188
	v_add_f32_e32 v129, 1.0, v129
	v_add_f32_e32 v188, 1.0, v188
	v_log_f32_e32 v129, v129
	v_log_f32_e32 v188, v188
	v_fmac_f32_e32 v51, 0x3f317218, v129
	v_fmac_f32_e32 v161, 0x3f317218, v188
	ds_read_b128 v[194:197], v10 offset:192
	ds_read_b128 v[198:201], v10 offset:208
	ds_read_b128 v[202:205], v10 offset:224
	ds_read_b128 v[206:209], v10 offset:240
	ds_read_b128 v[210:213], v10 offset:256
	ds_read_b128 v[214:217], v10 offset:272
	ds_read_b128 v[218:221], v10 offset:288
	ds_read_b128 v[236:239], v10 offset:304
	v_mul_f32_e32 v6, 0xbd800000, v51
	v_fmamk_f32 v8, v161, 0xbd800000, v6
	s_waitcnt lgkmcnt(4)
	v_pk_mul_f32 v[240:241], v[130:131], v[240:241]
	v_pk_mul_f32 v[194:195], v[130:131], v[194:195]
	v_pk_fma_f32 v[240:241], v[132:133], v[242:243], v[240:241]
	v_pk_fma_f32 v[194:195], v[132:133], v[196:197], v[194:195]
	v_pk_fma_f32 v[240:241], v[134:135], v[244:245], v[240:241]
	v_pk_fma_f32 v[194:195], v[134:135], v[198:199], v[194:195]
	v_pk_fma_f32 v[240:241], v[136:137], v[246:247], v[240:241]
	v_pk_fma_f32 v[194:195], v[136:137], v[200:201], v[194:195]
	v_pk_fma_f32 v[240:241], v[140:141], v[150:151], v[240:241]
	v_pk_fma_f32 v[194:195], v[140:141], v[202:203], v[194:195]
	v_pk_fma_f32 v[240:241], v[142:143], v[152:153], v[240:241]
	v_pk_fma_f32 v[194:195], v[142:143], v[204:205], v[194:195]
	v_pk_fma_f32 v[240:241], v[146:147], v[156:157], v[240:241]
	v_pk_fma_f32 v[194:195], v[146:147], v[206:207], v[194:195]
	v_pk_fma_f32 v[240:241], v[148:149], v[158:159], v[240:241]
	v_pk_fma_f32 v[194:195], v[148:149], v[208:209], v[194:195]
	v_add_f32_e32 v49, v240, v241
	v_add_f32_e32 v138, v194, v195
	v_add_f32_e32 v49, v122, v49
	v_add_f32_e32 v138, v122, v138
	v_max_f32_e64 v51, -v49, 0
	v_max_f32_e64 v161, -v138, 0
	v_mul_f32_e64 v129, |v49|, s13
	v_mul_f32_e64 v188, |v138|, s13
	v_exp_f32_e32 v129, v129
	v_exp_f32_e32 v188, v188
	v_add_f32_e32 v129, 1.0, v129
	v_add_f32_e32 v188, 1.0, v188
	v_log_f32_e32 v129, v129
	v_log_f32_e32 v188, v188
	v_fmac_f32_e32 v51, 0x3f317218, v129
	v_fmac_f32_e32 v161, 0x3f317218, v188
	ds_read_b128 v[240:243], v10 offset:320
	ds_read_b128 v[244:247], v10 offset:336
	ds_read_b128 v[150:153], v10 offset:352
	ds_read_b128 v[156:159], v10 offset:368
	ds_read_b128 v[194:197], v10 offset:384
	ds_read_b128 v[198:201], v10 offset:400
	ds_read_b128 v[202:205], v10 offset:416
	ds_read_b128 v[206:209], v10 offset:432
	v_fmamk_f32 v7, v51, 0xbd800000, v8
	v_fmamk_f32 v11, v161, 0xbd800000, v7
	s_waitcnt lgkmcnt(4)
	v_pk_mul_f32 v[210:211], v[130:131], v[210:211]
	v_pk_mul_f32 v[240:241], v[130:131], v[240:241]
	v_pk_fma_f32 v[210:211], v[132:133], v[212:213], v[210:211]
	v_pk_fma_f32 v[240:241], v[132:133], v[242:243], v[240:241]
	v_pk_fma_f32 v[210:211], v[134:135], v[214:215], v[210:211]
	v_pk_fma_f32 v[240:241], v[134:135], v[244:245], v[240:241]
	v_pk_fma_f32 v[210:211], v[136:137], v[216:217], v[210:211]
	v_pk_fma_f32 v[240:241], v[136:137], v[246:247], v[240:241]
	v_pk_fma_f32 v[210:211], v[140:141], v[218:219], v[210:211]
	v_pk_fma_f32 v[240:241], v[140:141], v[150:151], v[240:241]
	v_pk_fma_f32 v[210:211], v[142:143], v[220:221], v[210:211]
	v_pk_fma_f32 v[240:241], v[142:143], v[152:153], v[240:241]
	v_pk_fma_f32 v[210:211], v[146:147], v[236:237], v[210:211]
	v_pk_fma_f32 v[240:241], v[146:147], v[156:157], v[240:241]
	v_pk_fma_f32 v[210:211], v[148:149], v[238:239], v[210:211]
	v_pk_fma_f32 v[240:241], v[148:149], v[158:159], v[240:241]
	v_add_f32_e32 v49, v210, v211
	v_add_f32_e32 v138, v240, v241
	v_add_f32_e32 v49, v122, v49
	v_add_f32_e32 v138, v122, v138
	v_max_f32_e64 v51, -v49, 0
	v_max_f32_e64 v161, -v138, 0
	v_mul_f32_e64 v129, |v49|, s13
	v_mul_f32_e64 v188, |v138|, s13
	v_exp_f32_e32 v129, v129
	v_exp_f32_e32 v188, v188
	v_add_f32_e32 v129, 1.0, v129
	v_add_f32_e32 v188, 1.0, v188
	v_log_f32_e32 v129, v129
	v_log_f32_e32 v188, v188
	v_fmac_f32_e32 v51, 0x3f317218, v129
	v_fmac_f32_e32 v161, 0x3f317218, v188
	ds_read_b128 v[210:213], v10 offset:448
	ds_read_b128 v[214:217], v10 offset:464
	ds_read_b128 v[218:221], v10 offset:480
	ds_read_b128 v[236:239], v10 offset:496
	ds_read_b128 v[240:243], v10 offset:512
	ds_read_b128 v[244:247], v10 offset:528
	ds_read_b128 v[150:153], v10 offset:544
	ds_read_b128 v[156:159], v10 offset:560
	v_fmamk_f32 v9, v51, 0xbd800000, v11
	v_fmamk_f32 v13, v161, 0xbd800000, v9
	s_waitcnt lgkmcnt(4)
	v_pk_mul_f32 v[194:195], v[130:131], v[194:195]
	v_pk_mul_f32 v[210:211], v[130:131], v[210:211]
	v_pk_fma_f32 v[194:195], v[132:133], v[196:197], v[194:195]
	v_pk_fma_f32 v[210:211], v[132:133], v[212:213], v[210:211]
	v_pk_fma_f32 v[194:195], v[134:135], v[198:199], v[194:195]
	v_pk_fma_f32 v[210:211], v[134:135], v[214:215], v[210:211]
	v_pk_fma_f32 v[194:195], v[136:137], v[200:201], v[194:195]
	v_pk_fma_f32 v[210:211], v[136:137], v[216:217], v[210:211]
	v_pk_fma_f32 v[194:195], v[140:141], v[202:203], v[194:195]
	v_pk_fma_f32 v[210:211], v[140:141], v[218:219], v[210:211]
	v_pk_fma_f32 v[194:195], v[142:143], v[204:205], v[194:195]
	v_pk_fma_f32 v[210:211], v[142:143], v[220:221], v[210:211]
	v_pk_fma_f32 v[194:195], v[146:147], v[206:207], v[194:195]
	v_pk_fma_f32 v[210:211], v[146:147], v[236:237], v[210:211]
	v_pk_fma_f32 v[194:195], v[148:149], v[208:209], v[194:195]
	v_pk_fma_f32 v[210:211], v[148:149], v[238:239], v[210:211]
	v_add_f32_e32 v49, v194, v195
	v_add_f32_e32 v138, v210, v211
	v_add_f32_e32 v49, v122, v49
	v_add_f32_e32 v138, v122, v138
	v_max_f32_e64 v51, -v49, 0
	v_max_f32_e64 v161, -v138, 0
	v_mul_f32_e64 v129, |v49|, s13
	v_mul_f32_e64 v188, |v138|, s13
	v_exp_f32_e32 v129, v129
	v_exp_f32_e32 v188, v188
	v_add_f32_e32 v129, 1.0, v129
	v_add_f32_e32 v188, 1.0, v188
	v_log_f32_e32 v129, v129
	v_log_f32_e32 v188, v188
	v_fmac_f32_e32 v51, 0x3f317218, v129
	v_fmac_f32_e32 v161, 0x3f317218, v188
	ds_read_b128 v[194:197], v10 offset:576
	ds_read_b128 v[198:201], v10 offset:592
	ds_read_b128 v[202:205], v10 offset:608
	ds_read_b128 v[206:209], v10 offset:624
	ds_read_b128 v[210:213], v10 offset:640
	ds_read_b128 v[214:217], v10 offset:656
	ds_read_b128 v[218:221], v10 offset:672
	ds_read_b128 v[236:239], v10 offset:688
	v_fmamk_f32 v12, v51, 0xbd800000, v13
	v_fmamk_f32 v15, v161, 0xbd800000, v12
	s_waitcnt lgkmcnt(4)
	v_pk_mul_f32 v[240:241], v[130:131], v[240:241]
	v_pk_mul_f32 v[194:195], v[130:131], v[194:195]
	v_pk_fma_f32 v[240:241], v[132:133], v[242:243], v[240:241]
	v_pk_fma_f32 v[194:195], v[132:133], v[196:197], v[194:195]
	v_pk_fma_f32 v[240:241], v[134:135], v[244:245], v[240:241]
	v_pk_fma_f32 v[194:195], v[134:135], v[198:199], v[194:195]
	v_pk_fma_f32 v[240:241], v[136:137], v[246:247], v[240:241]
	v_pk_fma_f32 v[194:195], v[136:137], v[200:201], v[194:195]
	v_pk_fma_f32 v[240:241], v[140:141], v[150:151], v[240:241]
	v_pk_fma_f32 v[194:195], v[140:141], v[202:203], v[194:195]
	v_pk_fma_f32 v[240:241], v[142:143], v[152:153], v[240:241]
	v_pk_fma_f32 v[194:195], v[142:143], v[204:205], v[194:195]
	v_pk_fma_f32 v[240:241], v[146:147], v[156:157], v[240:241]
	v_pk_fma_f32 v[194:195], v[146:147], v[206:207], v[194:195]
	v_pk_fma_f32 v[240:241], v[148:149], v[158:159], v[240:241]
	v_pk_fma_f32 v[194:195], v[148:149], v[208:209], v[194:195]
	v_add_f32_e32 v49, v240, v241
	v_add_f32_e32 v138, v194, v195
	v_add_f32_e32 v49, v122, v49
	v_add_f32_e32 v138, v122, v138
	v_max_f32_e64 v51, -v49, 0
	v_max_f32_e64 v161, -v138, 0
	v_mul_f32_e64 v129, |v49|, s13
	v_mul_f32_e64 v188, |v138|, s13
	v_exp_f32_e32 v129, v129
	v_exp_f32_e32 v188, v188
	v_add_f32_e32 v129, 1.0, v129
	v_add_f32_e32 v188, 1.0, v188
	v_log_f32_e32 v129, v129
	v_log_f32_e32 v188, v188
	v_fmac_f32_e32 v51, 0x3f317218, v129
	v_fmac_f32_e32 v161, 0x3f317218, v188
	ds_read_b128 v[240:243], v10 offset:704
	ds_read_b128 v[244:247], v10 offset:720
	ds_read_b128 v[150:153], v10 offset:736
	ds_read_b128 v[156:159], v10 offset:752
	ds_read_b128 v[194:197], v10 offset:768
	ds_read_b128 v[198:201], v10 offset:784
	ds_read_b128 v[202:205], v10 offset:800
	ds_read_b128 v[206:209], v10 offset:816
	v_fmamk_f32 v14, v51, 0xbd800000, v15
	v_fmamk_f32 v17, v161, 0xbd800000, v14
	s_waitcnt lgkmcnt(4)
	v_pk_mul_f32 v[210:211], v[130:131], v[210:211]
	v_pk_mul_f32 v[240:241], v[130:131], v[240:241]
	v_pk_fma_f32 v[210:211], v[132:133], v[212:213], v[210:211]
	v_pk_fma_f32 v[240:241], v[132:133], v[242:243], v[240:241]
	v_pk_fma_f32 v[210:211], v[134:135], v[214:215], v[210:211]
	v_pk_fma_f32 v[240:241], v[134:135], v[244:245], v[240:241]
	v_pk_fma_f32 v[210:211], v[136:137], v[216:217], v[210:211]
	v_pk_fma_f32 v[240:241], v[136:137], v[246:247], v[240:241]
	v_pk_fma_f32 v[210:211], v[140:141], v[218:219], v[210:211]
	v_pk_fma_f32 v[240:241], v[140:141], v[150:151], v[240:241]
	v_pk_fma_f32 v[210:211], v[142:143], v[220:221], v[210:211]
	v_pk_fma_f32 v[240:241], v[142:143], v[152:153], v[240:241]
	v_pk_fma_f32 v[210:211], v[146:147], v[236:237], v[210:211]
	v_pk_fma_f32 v[240:241], v[146:147], v[156:157], v[240:241]
	v_pk_fma_f32 v[210:211], v[148:149], v[238:239], v[210:211]
	v_pk_fma_f32 v[240:241], v[148:149], v[158:159], v[240:241]
	v_add_f32_e32 v49, v210, v211
	v_add_f32_e32 v138, v240, v241
	v_add_f32_e32 v49, v122, v49
	v_add_f32_e32 v138, v122, v138
	v_max_f32_e64 v51, -v49, 0
	v_max_f32_e64 v161, -v138, 0
	v_mul_f32_e64 v129, |v49|, s13
	v_mul_f32_e64 v188, |v138|, s13
	v_exp_f32_e32 v129, v129
	v_exp_f32_e32 v188, v188
	v_add_f32_e32 v129, 1.0, v129
	v_add_f32_e32 v188, 1.0, v188
	v_log_f32_e32 v129, v129
	v_log_f32_e32 v188, v188
	v_fmac_f32_e32 v51, 0x3f317218, v129
	v_fmac_f32_e32 v161, 0x3f317218, v188
	ds_read_b128 v[210:213], v10 offset:832
	ds_read_b128 v[214:217], v10 offset:848
	ds_read_b128 v[218:221], v10 offset:864
	ds_read_b128 v[236:239], v10 offset:880
	ds_read_b128 v[240:243], v10 offset:896
	ds_read_b128 v[244:247], v10 offset:912
	ds_read_b128 v[150:153], v10 offset:928
	ds_read_b128 v[156:159], v10 offset:944
	v_fmamk_f32 v16, v51, 0xbd800000, v17
	v_fmamk_f32 v19, v161, 0xbd800000, v16
	s_waitcnt lgkmcnt(4)
	v_pk_mul_f32 v[194:195], v[130:131], v[194:195]
	v_pk_mul_f32 v[210:211], v[130:131], v[210:211]
	v_pk_fma_f32 v[194:195], v[132:133], v[196:197], v[194:195]
	v_pk_fma_f32 v[210:211], v[132:133], v[212:213], v[210:211]
	v_pk_fma_f32 v[194:195], v[134:135], v[198:199], v[194:195]
	v_pk_fma_f32 v[210:211], v[134:135], v[214:215], v[210:211]
	v_pk_fma_f32 v[194:195], v[136:137], v[200:201], v[194:195]
	v_pk_fma_f32 v[210:211], v[136:137], v[216:217], v[210:211]
	v_pk_fma_f32 v[194:195], v[140:141], v[202:203], v[194:195]
	v_pk_fma_f32 v[210:211], v[140:141], v[218:219], v[210:211]
	v_pk_fma_f32 v[194:195], v[142:143], v[204:205], v[194:195]
	v_pk_fma_f32 v[210:211], v[142:143], v[220:221], v[210:211]
	v_pk_fma_f32 v[194:195], v[146:147], v[206:207], v[194:195]
	v_pk_fma_f32 v[210:211], v[146:147], v[236:237], v[210:211]
	v_pk_fma_f32 v[194:195], v[148:149], v[208:209], v[194:195]
	v_pk_fma_f32 v[210:211], v[148:149], v[238:239], v[210:211]
	v_add_f32_e32 v49, v194, v195
	v_add_f32_e32 v138, v210, v211
	v_add_f32_e32 v49, v122, v49
	v_add_f32_e32 v138, v122, v138
	v_max_f32_e64 v51, -v49, 0
	v_max_f32_e64 v161, -v138, 0
	v_mul_f32_e64 v129, |v49|, s13
	v_mul_f32_e64 v188, |v138|, s13
	v_exp_f32_e32 v129, v129
	v_exp_f32_e32 v188, v188
	v_add_f32_e32 v129, 1.0, v129
	v_add_f32_e32 v188, 1.0, v188
	v_log_f32_e32 v129, v129
	v_log_f32_e32 v188, v188
	v_fmac_f32_e32 v51, 0x3f317218, v129
	v_fmac_f32_e32 v161, 0x3f317218, v188
	ds_read_b128 v[194:197], v10 offset:960
	ds_read_b128 v[198:201], v10 offset:976
	ds_read_b128 v[202:205], v10 offset:992
	ds_read_b128 v[206:209], v10 offset:1008
	ds_read_b128 v[210:213], v10 offset:1024
	ds_read_b128 v[214:217], v10 offset:1040
	ds_read_b128 v[218:221], v10 offset:1056
	ds_read_b128 v[236:239], v10 offset:1072
	v_fmamk_f32 v18, v51, 0xbd800000, v19
	v_fmamk_f32 v21, v161, 0xbd800000, v18
	s_waitcnt lgkmcnt(4)
	v_pk_mul_f32 v[240:241], v[130:131], v[240:241]
	v_pk_mul_f32 v[194:195], v[130:131], v[194:195]
	v_pk_fma_f32 v[240:241], v[132:133], v[242:243], v[240:241]
	v_pk_fma_f32 v[194:195], v[132:133], v[196:197], v[194:195]
	v_pk_fma_f32 v[240:241], v[134:135], v[244:245], v[240:241]
	v_pk_fma_f32 v[194:195], v[134:135], v[198:199], v[194:195]
	v_pk_fma_f32 v[240:241], v[136:137], v[246:247], v[240:241]
	v_pk_fma_f32 v[194:195], v[136:137], v[200:201], v[194:195]
	v_pk_fma_f32 v[240:241], v[140:141], v[150:151], v[240:241]
	v_pk_fma_f32 v[194:195], v[140:141], v[202:203], v[194:195]
	v_pk_fma_f32 v[240:241], v[142:143], v[152:153], v[240:241]
	v_pk_fma_f32 v[194:195], v[142:143], v[204:205], v[194:195]
	v_pk_fma_f32 v[240:241], v[146:147], v[156:157], v[240:241]
	v_pk_fma_f32 v[194:195], v[146:147], v[206:207], v[194:195]
	v_pk_fma_f32 v[240:241], v[148:149], v[158:159], v[240:241]
	v_pk_fma_f32 v[194:195], v[148:149], v[208:209], v[194:195]
	v_add_f32_e32 v49, v240, v241
	v_add_f32_e32 v138, v194, v195
	v_add_f32_e32 v49, v122, v49
	v_add_f32_e32 v138, v122, v138
	v_max_f32_e64 v51, -v49, 0
	v_max_f32_e64 v161, -v138, 0
	v_mul_f32_e64 v129, |v49|, s13
	v_mul_f32_e64 v188, |v138|, s13
	v_exp_f32_e32 v129, v129
	v_exp_f32_e32 v188, v188
	v_add_f32_e32 v129, 1.0, v129
	v_add_f32_e32 v188, 1.0, v188
	v_log_f32_e32 v129, v129
	v_log_f32_e32 v188, v188
	v_fmac_f32_e32 v51, 0x3f317218, v129
	v_fmac_f32_e32 v161, 0x3f317218, v188
	ds_read_b128 v[240:243], v10 offset:1088
	ds_read_b128 v[244:247], v10 offset:1104
	ds_read_b128 v[150:153], v10 offset:1120
	ds_read_b128 v[156:159], v10 offset:1136
	ds_read_b128 v[194:197], v10 offset:1152
	ds_read_b128 v[198:201], v10 offset:1168
	ds_read_b128 v[202:205], v10 offset:1184
	ds_read_b128 v[206:209], v10 offset:1200
	v_fmamk_f32 v20, v51, 0xbd800000, v21
	v_fmamk_f32 v23, v161, 0xbd800000, v20
	s_waitcnt lgkmcnt(4)
	v_pk_mul_f32 v[210:211], v[130:131], v[210:211]
	v_pk_mul_f32 v[240:241], v[130:131], v[240:241]
	v_pk_fma_f32 v[210:211], v[132:133], v[212:213], v[210:211]
	v_pk_fma_f32 v[240:241], v[132:133], v[242:243], v[240:241]
	v_pk_fma_f32 v[210:211], v[134:135], v[214:215], v[210:211]
	v_pk_fma_f32 v[240:241], v[134:135], v[244:245], v[240:241]
	v_pk_fma_f32 v[210:211], v[136:137], v[216:217], v[210:211]
	v_pk_fma_f32 v[240:241], v[136:137], v[246:247], v[240:241]
	v_pk_fma_f32 v[210:211], v[140:141], v[218:219], v[210:211]
	v_pk_fma_f32 v[240:241], v[140:141], v[150:151], v[240:241]
	v_pk_fma_f32 v[210:211], v[142:143], v[220:221], v[210:211]
	v_pk_fma_f32 v[240:241], v[142:143], v[152:153], v[240:241]
	v_pk_fma_f32 v[210:211], v[146:147], v[236:237], v[210:211]
	v_pk_fma_f32 v[240:241], v[146:147], v[156:157], v[240:241]
	v_pk_fma_f32 v[210:211], v[148:149], v[238:239], v[210:211]
	v_pk_fma_f32 v[240:241], v[148:149], v[158:159], v[240:241]
	v_add_f32_e32 v49, v210, v211
	v_add_f32_e32 v138, v240, v241
	v_add_f32_e32 v49, v122, v49
	v_add_f32_e32 v138, v122, v138
	v_max_f32_e64 v51, -v49, 0
	v_max_f32_e64 v161, -v138, 0
	v_mul_f32_e64 v129, |v49|, s13
	v_mul_f32_e64 v188, |v138|, s13
	v_exp_f32_e32 v129, v129
	v_exp_f32_e32 v188, v188
	v_add_f32_e32 v129, 1.0, v129
	v_add_f32_e32 v188, 1.0, v188
	v_log_f32_e32 v129, v129
	v_log_f32_e32 v188, v188
	v_fmac_f32_e32 v51, 0x3f317218, v129
	v_fmac_f32_e32 v161, 0x3f317218, v188
	ds_read_b128 v[210:213], v10 offset:1216
	ds_read_b128 v[214:217], v10 offset:1232
	ds_read_b128 v[218:221], v10 offset:1248
	ds_read_b128 v[236:239], v10 offset:1264
	ds_read_b128 v[240:243], v10 offset:1280
	ds_read_b128 v[244:247], v10 offset:1296
	ds_read_b128 v[150:153], v10 offset:1312
	ds_read_b128 v[156:159], v10 offset:1328
	v_fmamk_f32 v22, v51, 0xbd800000, v23
	v_fmamk_f32 v25, v161, 0xbd800000, v22
	s_waitcnt lgkmcnt(4)
	v_pk_mul_f32 v[194:195], v[130:131], v[194:195]
	v_pk_mul_f32 v[210:211], v[130:131], v[210:211]
	v_pk_fma_f32 v[194:195], v[132:133], v[196:197], v[194:195]
	v_pk_fma_f32 v[210:211], v[132:133], v[212:213], v[210:211]
	v_pk_fma_f32 v[194:195], v[134:135], v[198:199], v[194:195]
	v_pk_fma_f32 v[210:211], v[134:135], v[214:215], v[210:211]
	v_pk_fma_f32 v[194:195], v[136:137], v[200:201], v[194:195]
	v_pk_fma_f32 v[210:211], v[136:137], v[216:217], v[210:211]
	v_pk_fma_f32 v[194:195], v[140:141], v[202:203], v[194:195]
	v_pk_fma_f32 v[210:211], v[140:141], v[218:219], v[210:211]
	v_pk_fma_f32 v[194:195], v[142:143], v[204:205], v[194:195]
	v_pk_fma_f32 v[210:211], v[142:143], v[220:221], v[210:211]
	v_pk_fma_f32 v[194:195], v[146:147], v[206:207], v[194:195]
	v_pk_fma_f32 v[210:211], v[146:147], v[236:237], v[210:211]
	v_pk_fma_f32 v[194:195], v[148:149], v[208:209], v[194:195]
	v_pk_fma_f32 v[210:211], v[148:149], v[238:239], v[210:211]
	v_add_f32_e32 v49, v194, v195
	v_add_f32_e32 v138, v210, v211
	v_add_f32_e32 v49, v122, v49
	v_add_f32_e32 v138, v122, v138
	v_max_f32_e64 v51, -v49, 0
	v_max_f32_e64 v161, -v138, 0
	v_mul_f32_e64 v129, |v49|, s13
	v_mul_f32_e64 v188, |v138|, s13
	v_exp_f32_e32 v129, v129
	v_exp_f32_e32 v188, v188
	v_add_f32_e32 v129, 1.0, v129
	v_add_f32_e32 v188, 1.0, v188
	v_log_f32_e32 v129, v129
	v_log_f32_e32 v188, v188
	v_fmac_f32_e32 v51, 0x3f317218, v129
	v_fmac_f32_e32 v161, 0x3f317218, v188
	ds_read_b128 v[194:197], v10 offset:1344
	ds_read_b128 v[198:201], v10 offset:1360
	ds_read_b128 v[202:205], v10 offset:1376
	ds_read_b128 v[206:209], v10 offset:1392
	ds_read_b128 v[210:213], v10 offset:1408
	ds_read_b128 v[214:217], v10 offset:1424
	ds_read_b128 v[218:221], v10 offset:1440
	ds_read_b128 v[236:239], v10 offset:1456
	v_fmamk_f32 v24, v51, 0xbd800000, v25
	v_fmamk_f32 v27, v161, 0xbd800000, v24
	s_waitcnt lgkmcnt(4)
	v_pk_mul_f32 v[240:241], v[130:131], v[240:241]
	v_pk_mul_f32 v[194:195], v[130:131], v[194:195]
	v_pk_fma_f32 v[240:241], v[132:133], v[242:243], v[240:241]
	v_pk_fma_f32 v[194:195], v[132:133], v[196:197], v[194:195]
	v_pk_fma_f32 v[240:241], v[134:135], v[244:245], v[240:241]
	v_pk_fma_f32 v[194:195], v[134:135], v[198:199], v[194:195]
	v_pk_fma_f32 v[240:241], v[136:137], v[246:247], v[240:241]
	v_pk_fma_f32 v[194:195], v[136:137], v[200:201], v[194:195]
	v_pk_fma_f32 v[240:241], v[140:141], v[150:151], v[240:241]
	v_pk_fma_f32 v[194:195], v[140:141], v[202:203], v[194:195]
	v_pk_fma_f32 v[240:241], v[142:143], v[152:153], v[240:241]
	v_pk_fma_f32 v[194:195], v[142:143], v[204:205], v[194:195]
	v_pk_fma_f32 v[240:241], v[146:147], v[156:157], v[240:241]
	v_pk_fma_f32 v[194:195], v[146:147], v[206:207], v[194:195]
	v_pk_fma_f32 v[240:241], v[148:149], v[158:159], v[240:241]
	v_pk_fma_f32 v[194:195], v[148:149], v[208:209], v[194:195]
	v_add_f32_e32 v49, v240, v241
	v_add_f32_e32 v138, v194, v195
	v_add_f32_e32 v49, v122, v49
	v_add_f32_e32 v138, v122, v138
	v_max_f32_e64 v51, -v49, 0
	v_max_f32_e64 v161, -v138, 0
	v_mul_f32_e64 v129, |v49|, s13
	v_mul_f32_e64 v188, |v138|, s13
	v_exp_f32_e32 v129, v129
	v_exp_f32_e32 v188, v188
	v_add_f32_e32 v129, 1.0, v129
	v_add_f32_e32 v188, 1.0, v188
	v_log_f32_e32 v129, v129
	v_log_f32_e32 v188, v188
	v_fmac_f32_e32 v51, 0x3f317218, v129
	v_fmac_f32_e32 v161, 0x3f317218, v188
	ds_read_b128 v[240:243], v10 offset:1472
	ds_read_b128 v[244:247], v10 offset:1488
	ds_read_b128 v[150:153], v10 offset:1504
	ds_read_b128 v[156:159], v10 offset:1520
	ds_read_b128 v[194:197], v10 offset:1536
	ds_read_b128 v[198:201], v10 offset:1552
	ds_read_b128 v[202:205], v10 offset:1568
	ds_read_b128 v[206:209], v10 offset:1584
	v_fmamk_f32 v26, v51, 0xbd800000, v27
	v_fmamk_f32 v29, v161, 0xbd800000, v26
	s_waitcnt lgkmcnt(4)
	v_pk_mul_f32 v[210:211], v[130:131], v[210:211]
	v_pk_mul_f32 v[240:241], v[130:131], v[240:241]
	v_pk_fma_f32 v[210:211], v[132:133], v[212:213], v[210:211]
	v_pk_fma_f32 v[240:241], v[132:133], v[242:243], v[240:241]
	v_pk_fma_f32 v[210:211], v[134:135], v[214:215], v[210:211]
	v_pk_fma_f32 v[240:241], v[134:135], v[244:245], v[240:241]
	v_pk_fma_f32 v[210:211], v[136:137], v[216:217], v[210:211]
	v_pk_fma_f32 v[240:241], v[136:137], v[246:247], v[240:241]
	v_pk_fma_f32 v[210:211], v[140:141], v[218:219], v[210:211]
	v_pk_fma_f32 v[240:241], v[140:141], v[150:151], v[240:241]
	v_pk_fma_f32 v[210:211], v[142:143], v[220:221], v[210:211]
	v_pk_fma_f32 v[240:241], v[142:143], v[152:153], v[240:241]
	v_pk_fma_f32 v[210:211], v[146:147], v[236:237], v[210:211]
	v_pk_fma_f32 v[240:241], v[146:147], v[156:157], v[240:241]
	v_pk_fma_f32 v[210:211], v[148:149], v[238:239], v[210:211]
	v_pk_fma_f32 v[240:241], v[148:149], v[158:159], v[240:241]
	v_add_f32_e32 v49, v210, v211
	v_add_f32_e32 v138, v240, v241
	v_add_f32_e32 v49, v122, v49
	v_add_f32_e32 v138, v122, v138
	v_max_f32_e64 v51, -v49, 0
	v_max_f32_e64 v161, -v138, 0
	v_mul_f32_e64 v129, |v49|, s13
	v_mul_f32_e64 v188, |v138|, s13
	v_exp_f32_e32 v129, v129
	v_exp_f32_e32 v188, v188
	v_add_f32_e32 v129, 1.0, v129
	v_add_f32_e32 v188, 1.0, v188
	v_log_f32_e32 v129, v129
	v_log_f32_e32 v188, v188
	v_fmac_f32_e32 v51, 0x3f317218, v129
	v_fmac_f32_e32 v161, 0x3f317218, v188
	ds_read_b128 v[210:213], v10 offset:1600
	ds_read_b128 v[214:217], v10 offset:1616
	ds_read_b128 v[218:221], v10 offset:1632
	ds_read_b128 v[236:239], v10 offset:1648
	ds_read_b128 v[240:243], v10 offset:1664
	ds_read_b128 v[244:247], v10 offset:1680
	ds_read_b128 v[150:153], v10 offset:1696
	ds_read_b128 v[156:159], v10 offset:1712
	v_fmamk_f32 v28, v51, 0xbd800000, v29
	v_fmamk_f32 v31, v161, 0xbd800000, v28
	s_waitcnt lgkmcnt(4)
	v_pk_mul_f32 v[194:195], v[130:131], v[194:195]
	v_pk_mul_f32 v[210:211], v[130:131], v[210:211]
	v_pk_fma_f32 v[194:195], v[132:133], v[196:197], v[194:195]
	v_pk_fma_f32 v[210:211], v[132:133], v[212:213], v[210:211]
	v_pk_fma_f32 v[194:195], v[134:135], v[198:199], v[194:195]
	v_pk_fma_f32 v[210:211], v[134:135], v[214:215], v[210:211]
	v_pk_fma_f32 v[194:195], v[136:137], v[200:201], v[194:195]
	v_pk_fma_f32 v[210:211], v[136:137], v[216:217], v[210:211]
	v_pk_fma_f32 v[194:195], v[140:141], v[202:203], v[194:195]
	v_pk_fma_f32 v[210:211], v[140:141], v[218:219], v[210:211]
	v_pk_fma_f32 v[194:195], v[142:143], v[204:205], v[194:195]
	v_pk_fma_f32 v[210:211], v[142:143], v[220:221], v[210:211]
	v_pk_fma_f32 v[194:195], v[146:147], v[206:207], v[194:195]
	v_pk_fma_f32 v[210:211], v[146:147], v[236:237], v[210:211]
	v_pk_fma_f32 v[194:195], v[148:149], v[208:209], v[194:195]
	v_pk_fma_f32 v[210:211], v[148:149], v[238:239], v[210:211]
	v_add_f32_e32 v49, v194, v195
	v_add_f32_e32 v138, v210, v211
	v_add_f32_e32 v49, v122, v49
	v_add_f32_e32 v138, v122, v138
	v_max_f32_e64 v51, -v49, 0
	v_max_f32_e64 v161, -v138, 0
	v_mul_f32_e64 v129, |v49|, s13
	v_mul_f32_e64 v188, |v138|, s13
	v_exp_f32_e32 v129, v129
	v_exp_f32_e32 v188, v188
	v_add_f32_e32 v129, 1.0, v129
	v_add_f32_e32 v188, 1.0, v188
	v_log_f32_e32 v129, v129
	v_log_f32_e32 v188, v188
	v_fmac_f32_e32 v51, 0x3f317218, v129
	v_fmac_f32_e32 v161, 0x3f317218, v188
	ds_read_b128 v[194:197], v10 offset:1728
	ds_read_b128 v[198:201], v10 offset:1744
	ds_read_b128 v[202:205], v10 offset:1760
	ds_read_b128 v[206:209], v10 offset:1776
	ds_read_b128 v[210:213], v10 offset:1792
	ds_read_b128 v[214:217], v10 offset:1808
	ds_read_b128 v[218:221], v10 offset:1824
	ds_read_b128 v[236:239], v10 offset:1840
	v_fmamk_f32 v30, v51, 0xbd800000, v31
	v_fmamk_f32 v33, v161, 0xbd800000, v30
	s_waitcnt lgkmcnt(4)
	v_pk_mul_f32 v[240:241], v[130:131], v[240:241]
	v_pk_mul_f32 v[194:195], v[130:131], v[194:195]
	v_pk_fma_f32 v[240:241], v[132:133], v[242:243], v[240:241]
	v_pk_fma_f32 v[194:195], v[132:133], v[196:197], v[194:195]
	v_pk_fma_f32 v[240:241], v[134:135], v[244:245], v[240:241]
	v_pk_fma_f32 v[194:195], v[134:135], v[198:199], v[194:195]
	v_pk_fma_f32 v[240:241], v[136:137], v[246:247], v[240:241]
	v_pk_fma_f32 v[194:195], v[136:137], v[200:201], v[194:195]
	v_pk_fma_f32 v[240:241], v[140:141], v[150:151], v[240:241]
	v_pk_fma_f32 v[194:195], v[140:141], v[202:203], v[194:195]
	v_pk_fma_f32 v[240:241], v[142:143], v[152:153], v[240:241]
	v_pk_fma_f32 v[194:195], v[142:143], v[204:205], v[194:195]
	v_pk_fma_f32 v[240:241], v[146:147], v[156:157], v[240:241]
	v_pk_fma_f32 v[194:195], v[146:147], v[206:207], v[194:195]
	v_pk_fma_f32 v[240:241], v[148:149], v[158:159], v[240:241]
	v_pk_fma_f32 v[194:195], v[148:149], v[208:209], v[194:195]
	v_add_f32_e32 v49, v240, v241
	v_add_f32_e32 v138, v194, v195
	v_add_f32_e32 v49, v122, v49
	v_add_f32_e32 v138, v122, v138
	v_max_f32_e64 v51, -v49, 0
	v_max_f32_e64 v161, -v138, 0
	v_mul_f32_e64 v129, |v49|, s13
	v_mul_f32_e64 v188, |v138|, s13
	v_exp_f32_e32 v129, v129
	v_exp_f32_e32 v188, v188
	v_add_f32_e32 v129, 1.0, v129
	v_add_f32_e32 v188, 1.0, v188
	v_log_f32_e32 v129, v129
	v_log_f32_e32 v188, v188
	v_fmac_f32_e32 v51, 0x3f317218, v129
	v_fmac_f32_e32 v161, 0x3f317218, v188
	ds_read_b128 v[240:243], v10 offset:1856
	ds_read_b128 v[244:247], v10 offset:1872
	ds_read_b128 v[150:153], v10 offset:1888
	ds_read_b128 v[156:159], v10 offset:1904
	ds_read_b128 v[194:197], v10 offset:1920
	ds_read_b128 v[198:201], v10 offset:1936
	ds_read_b128 v[202:205], v10 offset:1952
	ds_read_b128 v[206:209], v10 offset:1968
	v_fmamk_f32 v32, v51, 0xbd800000, v33
	v_fmamk_f32 v35, v161, 0xbd800000, v32
	s_waitcnt lgkmcnt(4)
	v_pk_mul_f32 v[210:211], v[130:131], v[210:211]
	v_pk_mul_f32 v[240:241], v[130:131], v[240:241]
	v_pk_fma_f32 v[210:211], v[132:133], v[212:213], v[210:211]
	v_pk_fma_f32 v[240:241], v[132:133], v[242:243], v[240:241]
	v_pk_fma_f32 v[210:211], v[134:135], v[214:215], v[210:211]
	v_pk_fma_f32 v[240:241], v[134:135], v[244:245], v[240:241]
	v_pk_fma_f32 v[210:211], v[136:137], v[216:217], v[210:211]
	v_pk_fma_f32 v[240:241], v[136:137], v[246:247], v[240:241]
	v_pk_fma_f32 v[210:211], v[140:141], v[218:219], v[210:211]
	v_pk_fma_f32 v[240:241], v[140:141], v[150:151], v[240:241]
	v_pk_fma_f32 v[210:211], v[142:143], v[220:221], v[210:211]
	v_pk_fma_f32 v[240:241], v[142:143], v[152:153], v[240:241]
	v_pk_fma_f32 v[210:211], v[146:147], v[236:237], v[210:211]
	v_pk_fma_f32 v[240:241], v[146:147], v[156:157], v[240:241]
	v_pk_fma_f32 v[210:211], v[148:149], v[238:239], v[210:211]
	v_pk_fma_f32 v[240:241], v[148:149], v[158:159], v[240:241]
	v_add_f32_e32 v49, v210, v211
	v_add_f32_e32 v138, v240, v241
	v_add_f32_e32 v49, v122, v49
	v_add_f32_e32 v138, v122, v138
	v_max_f32_e64 v51, -v49, 0
	v_max_f32_e64 v161, -v138, 0
	v_mul_f32_e64 v129, |v49|, s13
	v_mul_f32_e64 v188, |v138|, s13
	v_exp_f32_e32 v129, v129
	v_exp_f32_e32 v188, v188
	v_add_f32_e32 v129, 1.0, v129
	v_add_f32_e32 v188, 1.0, v188
	v_log_f32_e32 v129, v129
	v_log_f32_e32 v188, v188
	v_fmac_f32_e32 v51, 0x3f317218, v129
	v_fmac_f32_e32 v161, 0x3f317218, v188
	ds_read_b128 v[210:213], v10 offset:1984
	ds_read_b128 v[214:217], v10 offset:2000
	ds_read_b128 v[218:221], v10 offset:2016
	ds_read_b128 v[236:239], v10 offset:2032
	v_fmamk_f32 v34, v51, 0xbd800000, v35
	v_fmamk_f32 v42, v161, 0xbd800000, v34
	s_waitcnt lgkmcnt(0)
	v_pk_mul_f32 v[194:195], v[130:131], v[194:195]
	v_pk_mul_f32 v[210:211], v[130:131], v[210:211]
	v_pk_fma_f32 v[194:195], v[132:133], v[196:197], v[194:195]
	v_pk_fma_f32 v[210:211], v[132:133], v[212:213], v[210:211]
	v_pk_fma_f32 v[194:195], v[134:135], v[198:199], v[194:195]
	v_pk_fma_f32 v[210:211], v[134:135], v[214:215], v[210:211]
	v_pk_fma_f32 v[194:195], v[136:137], v[200:201], v[194:195]
	v_pk_fma_f32 v[210:211], v[136:137], v[216:217], v[210:211]
	v_pk_fma_f32 v[194:195], v[140:141], v[202:203], v[194:195]
	v_pk_fma_f32 v[210:211], v[140:141], v[218:219], v[210:211]
	v_pk_fma_f32 v[194:195], v[142:143], v[204:205], v[194:195]
	v_pk_fma_f32 v[210:211], v[142:143], v[220:221], v[210:211]
	v_pk_fma_f32 v[194:195], v[146:147], v[206:207], v[194:195]
	v_pk_fma_f32 v[210:211], v[146:147], v[236:237], v[210:211]
	v_pk_fma_f32 v[194:195], v[148:149], v[208:209], v[194:195]
	v_pk_fma_f32 v[210:211], v[148:149], v[238:239], v[210:211]
	v_add_f32_e32 v49, v194, v195
	v_add_f32_e32 v138, v210, v211
	v_add_f32_e32 v49, v122, v49
	v_add_f32_e32 v138, v122, v138
	v_max_f32_e64 v51, -v49, 0
	v_max_f32_e64 v161, -v138, 0
	v_mul_f32_e64 v129, |v49|, s13
	v_mul_f32_e64 v188, |v138|, s13
	v_exp_f32_e32 v129, v129
	v_exp_f32_e32 v188, v188
	v_add_f32_e32 v129, 1.0, v129
	v_add_f32_e32 v188, 1.0, v188
	v_log_f32_e32 v129, v129
	v_log_f32_e32 v188, v188
	v_fmac_f32_e32 v51, 0x3f317218, v129
	v_fmac_f32_e32 v161, 0x3f317218, v188
	v_fmamk_f32 v36, v51, 0xbd800000, v42
	v_fmamk_f32 v43, v161, 0xbd800000, v36
	v_lshl_add_u32 v10, v38, 2, s0
	ds_write_b32 v10, v43
	v_add_u32_e32 v10, s0, v40
	s_waitcnt lgkmcnt(0)
	s_barrier
	ds_read2st64_b32 v[46:47], v10 offset1:4
	s_movk_i32 s0, 0x100
	v_cmp_gt_u32_e32 vcc, s0, v38
	v_readlane_b32 s0, v254, 63
	v_readlane_b32 s1, v255, 0
	s_waitcnt lgkmcnt(0)
	v_cndmask_b32_e64 v40, v46, 0, vcc
	v_add_f32_e32 v44, v6, v40
	v_add_f32_e32 v10, v46, v47
	v_mul_f32_e32 v47, 0x3fb8aa3b, v44
	v_exp_f32_e32 v47, v47
	v_lshlrev_b32_e32 v6, 16, v128
	v_cndmask_b32_e64 v37, v10, 0, s[0:1]
	v_mul_f32_e32 v6, 0x3e000000, v6
	v_mul_f32_e32 v6, v6, v47
	v_sub_f32_e32 v44, v37, v44
	v_mul_f32_e32 v44, 0x3fb8aa3b, v44
	v_cvt_pk_bf16_f32 v47, v6, v6
	v_mul_i32_i24_e32 v6, 0x2100, v121
	v_exp_f32_e32 v44, v44
	v_or_b32_sdwa v6, v6, v38 dst_sel:DWORD dst_unused:UNUSED_PAD src0_sel:DWORD src1_sel:BYTE_0
	v_lshl_add_u32 v6, v6, 1, 0
	v_add_f32_e32 v8, v8, v40
	v_lshlrev_b32_e32 v46, 16, v127
	ds_write_b16_d16_hi v6, v47
	v_mul_f32_e32 v47, 0x3fb8aa3b, v8
	v_mul_f32_e32 v44, v44, v46
	v_exp_f32_e32 v47, v47
	v_cvt_pk_bf16_f32 v44, v44, v44
	v_lshlrev_b32_e32 v46, 16, v126
	v_mul_f32_e32 v46, 0x3e000000, v46
	v_sub_f32_e32 v8, v37, v8
	v_mul_f32_e32 v46, v46, v47
	v_mul_f32_e32 v8, 0x3fb8aa3b, v8
	v_exp_f32_e32 v8, v8
	v_cvt_pk_bf16_f32 v46, v46, v46
	v_add_f32_e32 v7, v7, v40
	ds_write_b16_d16_hi v6, v46 offset:528
	v_mul_f32_e32 v46, 0x3fb8aa3b, v7
	v_sub_f32_e32 v7, v37, v7
	ds_write_b16_d16_hi v6, v44 offset:33792
	v_lshlrev_b32_e32 v44, 16, v125
	v_mul_f32_e32 v7, 0x3fb8aa3b, v7
	v_mul_f32_e32 v8, v8, v44
	v_exp_f32_e32 v7, v7
	v_exp_f32_e32 v46, v46
	v_cvt_pk_bf16_f32 v8, v8, v8
	ds_write_b16_d16_hi v6, v8 offset:34320
	v_lshlrev_b32_e32 v8, 16, v123
	v_lshlrev_b32_e32 v44, 16, v124
	v_mul_f32_e32 v44, 0x3e000000, v44
	v_mul_f32_e32 v7, v7, v8
	v_mul_f32_e32 v44, v44, v46
	v_cvt_pk_bf16_f32 v7, v7, v7
	v_cvt_pk_bf16_f32 v44, v44, v44
	ds_write_b16_d16_hi v6, v7 offset:34848
	v_add_f32_e32 v7, v11, v40
	ds_write_b16_d16_hi v6, v44 offset:1056
	v_mul_f32_e32 v44, 0x3fb8aa3b, v7
	v_sub_f32_e32 v7, v37, v7
	v_mul_f32_e32 v7, 0x3fb8aa3b, v7
	v_exp_f32_e32 v7, v7
	v_exp_f32_e32 v44, v44
	v_lshlrev_b32_e32 v8, 16, v118
	v_lshlrev_b32_e32 v11, 16, v119
	v_mul_f32_e32 v11, 0x3e000000, v11
	v_mul_f32_e32 v7, v7, v8
	v_mul_f32_e32 v11, v11, v44
	v_cvt_pk_bf16_f32 v7, v7, v7
	v_cvt_pk_bf16_f32 v11, v11, v11
	ds_write_b16_d16_hi v6, v7 offset:35376
	v_add_f32_e32 v7, v9, v40
	ds_write_b16_d16_hi v6, v11 offset:1584
	v_mul_f32_e32 v11, 0x3fb8aa3b, v7
	v_sub_f32_e32 v7, v37, v7
	v_mul_f32_e32 v7, 0x3fb8aa3b, v7
	v_exp_f32_e32 v7, v7
	v_exp_f32_e32 v11, v11
	v_lshlrev_b32_e32 v8, 16, v110
	v_lshlrev_b32_e32 v9, 16, v111
	v_mul_f32_e32 v7, v7, v8
	v_mul_f32_e32 v9, 0x3e000000, v9
	v_mul_f32_e32 v9, v9, v11
	v_cvt_pk_bf16_f32 v7, v7, v7
	ds_write_b16_d16_hi v6, v7 offset:35904
	v_add_f32_e32 v7, v13, v40
	v_cvt_pk_bf16_f32 v9, v9, v9
	v_mul_f32_e32 v11, 0x3fb8aa3b, v7
	v_sub_f32_e32 v7, v37, v7
	v_mul_f32_e32 v7, 0x3fb8aa3b, v7
	v_exp_f32_e32 v7, v7
	v_exp_f32_e32 v11, v11
	v_lshlrev_b32_e32 v8, 16, v102
	ds_write_b16_d16_hi v6, v9 offset:2112
	v_lshlrev_b32_e32 v9, 16, v103
	v_mul_f32_e32 v7, v7, v8
	v_mul_f32_e32 v9, 0x3e000000, v9
	v_mul_f32_e32 v9, v9, v11
	v_cvt_pk_bf16_f32 v7, v7, v7
	ds_write_b16_d16_hi v6, v7 offset:36432
	v_add_f32_e32 v7, v12, v40
	v_cvt_pk_bf16_f32 v9, v9, v9
	v_mul_f32_e32 v11, 0x3fb8aa3b, v7
	v_sub_f32_e32 v7, v37, v7
	v_mul_f32_e32 v7, 0x3fb8aa3b, v7
	v_exp_f32_e32 v7, v7
	v_exp_f32_e32 v11, v11
	v_lshlrev_b32_e32 v8, 16, v97
	ds_write_b16_d16_hi v6, v9 offset:2640
	v_lshlrev_b32_e32 v9, 16, v98
	v_mul_f32_e32 v7, v7, v8
	v_mul_f32_e32 v9, 0x3e000000, v9
	v_mul_f32_e32 v9, v9, v11
	v_cvt_pk_bf16_f32 v7, v7, v7
	ds_write_b16_d16_hi v6, v7 offset:36960
	v_add_f32_e32 v7, v15, v40
	v_cvt_pk_bf16_f32 v9, v9, v9
	v_mul_f32_e32 v11, 0x3fb8aa3b, v7
	v_sub_f32_e32 v7, v37, v7
	v_mul_f32_e32 v7, 0x3fb8aa3b, v7
	v_exp_f32_e32 v7, v7
	v_exp_f32_e32 v11, v11
	v_lshlrev_b32_e32 v8, 16, v95
	ds_write_b16_d16_hi v6, v9 offset:3168
	v_lshlrev_b32_e32 v9, 16, v96
	v_mul_f32_e32 v7, v7, v8
	v_mul_f32_e32 v9, 0x3e000000, v9
	v_mul_f32_e32 v9, v9, v11
	v_cvt_pk_bf16_f32 v7, v7, v7
	ds_write_b16_d16_hi v6, v7 offset:37488
	v_add_f32_e32 v7, v14, v40
	v_cvt_pk_bf16_f32 v9, v9, v9
	v_mul_f32_e32 v11, 0x3fb8aa3b, v7
	v_sub_f32_e32 v7, v37, v7
	v_mul_f32_e32 v7, 0x3fb8aa3b, v7
	v_exp_f32_e32 v7, v7
	v_exp_f32_e32 v11, v11
	v_lshlrev_b32_e32 v8, 16, v93
	ds_write_b16_d16_hi v6, v9 offset:3696
	v_lshlrev_b32_e32 v9, 16, v94
	v_mul_f32_e32 v7, v7, v8
	v_mul_f32_e32 v9, 0x3e000000, v9
	v_mul_f32_e32 v9, v9, v11
	v_cvt_pk_bf16_f32 v7, v7, v7
	ds_write_b16_d16_hi v6, v7 offset:38016
	v_add_f32_e32 v7, v17, v40
	v_cvt_pk_bf16_f32 v9, v9, v9
	v_mul_f32_e32 v11, 0x3fb8aa3b, v7
	v_sub_f32_e32 v7, v37, v7
	v_mul_f32_e32 v7, 0x3fb8aa3b, v7
	v_exp_f32_e32 v7, v7
	v_exp_f32_e32 v11, v11
	v_lshlrev_b32_e32 v8, 16, v91
	ds_write_b16_d16_hi v6, v9 offset:4224
	v_lshlrev_b32_e32 v9, 16, v92
	v_mul_f32_e32 v7, v7, v8
	v_mul_f32_e32 v9, 0x3e000000, v9
	v_mul_f32_e32 v9, v9, v11
	v_cvt_pk_bf16_f32 v7, v7, v7
	ds_write_b16_d16_hi v6, v7 offset:38544
	v_add_f32_e32 v7, v16, v40
	v_cvt_pk_bf16_f32 v9, v9, v9
	v_mul_f32_e32 v11, 0x3fb8aa3b, v7
	v_sub_f32_e32 v7, v37, v7
	v_mul_f32_e32 v7, 0x3fb8aa3b, v7
	v_exp_f32_e32 v7, v7
	v_exp_f32_e32 v11, v11
	v_lshlrev_b32_e32 v8, 16, v89
	ds_write_b16_d16_hi v6, v9 offset:4752
	v_lshlrev_b32_e32 v9, 16, v90
	v_mul_f32_e32 v7, v7, v8
	v_mul_f32_e32 v9, 0x3e000000, v9
	v_mul_f32_e32 v9, v9, v11
	v_cvt_pk_bf16_f32 v7, v7, v7
	ds_write_b16_d16_hi v6, v7 offset:39072
	v_add_f32_e32 v7, v19, v40
	v_cvt_pk_bf16_f32 v9, v9, v9
	v_mul_f32_e32 v11, 0x3fb8aa3b, v7
	v_sub_f32_e32 v7, v37, v7
	v_mul_f32_e32 v7, 0x3fb8aa3b, v7
	v_exp_f32_e32 v7, v7
	v_exp_f32_e32 v11, v11
	v_lshlrev_b32_e32 v8, 16, v87
	ds_write_b16_d16_hi v6, v9 offset:5280
	v_lshlrev_b32_e32 v9, 16, v88
	v_mul_f32_e32 v7, v7, v8
	v_mul_f32_e32 v9, 0x3e000000, v9
	v_mul_f32_e32 v9, v9, v11
	v_cvt_pk_bf16_f32 v7, v7, v7
	ds_write_b16_d16_hi v6, v7 offset:39600
	v_add_f32_e32 v7, v18, v40
	v_cvt_pk_bf16_f32 v9, v9, v9
	v_mul_f32_e32 v11, 0x3fb8aa3b, v7
	v_sub_f32_e32 v7, v37, v7
	v_mul_f32_e32 v7, 0x3fb8aa3b, v7
	v_exp_f32_e32 v7, v7
	v_exp_f32_e32 v11, v11
	v_lshlrev_b32_e32 v8, 16, v85
	ds_write_b16_d16_hi v6, v9 offset:5808
	v_lshlrev_b32_e32 v9, 16, v86
	v_mul_f32_e32 v7, v7, v8
	v_mul_f32_e32 v9, 0x3e000000, v9
	v_mul_f32_e32 v9, v9, v11
	v_cvt_pk_bf16_f32 v7, v7, v7
	ds_write_b16_d16_hi v6, v7 offset:40128
	v_add_f32_e32 v7, v21, v40
	v_cvt_pk_bf16_f32 v9, v9, v9
	v_mul_f32_e32 v11, 0x3fb8aa3b, v7
	v_sub_f32_e32 v7, v37, v7
	v_mul_f32_e32 v7, 0x3fb8aa3b, v7
	v_exp_f32_e32 v7, v7
	v_exp_f32_e32 v11, v11
	v_lshlrev_b32_e32 v8, 16, v84
	ds_write_b16_d16_hi v6, v9 offset:6336
	v_lshlrev_b32_e32 v9, 16, v83
	v_mul_f32_e32 v7, v7, v8
	v_mul_f32_e32 v9, 0x3e000000, v9
	v_mul_f32_e32 v9, v9, v11
	v_cvt_pk_bf16_f32 v7, v7, v7
	ds_write_b16_d16_hi v6, v7 offset:40656
	v_add_f32_e32 v7, v20, v40
	v_cvt_pk_bf16_f32 v9, v9, v9
	v_mul_f32_e32 v11, 0x3fb8aa3b, v7
	v_sub_f32_e32 v7, v37, v7
	v_mul_f32_e32 v7, 0x3fb8aa3b, v7
	v_exp_f32_e32 v7, v7
	v_exp_f32_e32 v11, v11
	v_lshlrev_b32_e32 v8, 16, v82
	ds_write_b16_d16_hi v6, v9 offset:6864
	v_lshlrev_b32_e32 v9, 16, v81
	v_mul_f32_e32 v7, v7, v8
	v_mul_f32_e32 v9, 0x3e000000, v9
	v_mul_f32_e32 v9, v9, v11
	v_cvt_pk_bf16_f32 v7, v7, v7
	ds_write_b16_d16_hi v6, v7 offset:41184
	v_add_f32_e32 v7, v23, v40
	v_cvt_pk_bf16_f32 v9, v9, v9
	v_mul_f32_e32 v11, 0x3fb8aa3b, v7
	v_sub_f32_e32 v7, v37, v7
	v_mul_f32_e32 v7, 0x3fb8aa3b, v7
	v_exp_f32_e32 v7, v7
	v_exp_f32_e32 v11, v11
	v_lshlrev_b32_e32 v8, 16, v80
	ds_write_b16_d16_hi v6, v9 offset:7392
	v_lshlrev_b32_e32 v9, 16, v79
	v_mul_f32_e32 v7, v7, v8
	v_mul_f32_e32 v9, 0x3e000000, v9
	v_mul_f32_e32 v9, v9, v11
	v_cvt_pk_bf16_f32 v7, v7, v7
	ds_write_b16_d16_hi v6, v7 offset:41712
	v_add_f32_e32 v7, v22, v40
	v_cvt_pk_bf16_f32 v9, v9, v9
	v_mul_f32_e32 v11, 0x3fb8aa3b, v7
	v_sub_f32_e32 v7, v37, v7
	v_mul_f32_e32 v7, 0x3fb8aa3b, v7
	v_exp_f32_e32 v7, v7
	v_exp_f32_e32 v11, v11
	v_lshlrev_b32_e32 v8, 16, v78
	ds_write_b16_d16_hi v6, v9 offset:7920
	v_lshlrev_b32_e32 v9, 16, v77
	v_mul_f32_e32 v7, v7, v8
	v_mul_f32_e32 v9, 0x3e000000, v9
	v_mul_f32_e32 v9, v9, v11
	v_cvt_pk_bf16_f32 v7, v7, v7
	ds_write_b16_d16_hi v6, v7 offset:42240
	v_add_f32_e32 v7, v25, v40
	v_cvt_pk_bf16_f32 v9, v9, v9
	v_mul_f32_e32 v11, 0x3fb8aa3b, v7
	v_sub_f32_e32 v7, v37, v7
	v_mul_f32_e32 v7, 0x3fb8aa3b, v7
	v_exp_f32_e32 v7, v7
	v_exp_f32_e32 v11, v11
	v_lshlrev_b32_e32 v8, 16, v76
	ds_write_b16_d16_hi v6, v9 offset:8448
	v_lshlrev_b32_e32 v9, 16, v75
	v_mul_f32_e32 v7, v7, v8
	v_mul_f32_e32 v9, 0x3e000000, v9
	v_mul_f32_e32 v9, v9, v11
	v_cvt_pk_bf16_f32 v7, v7, v7
	ds_write_b16_d16_hi v6, v7 offset:42768
	v_add_f32_e32 v7, v24, v40
	v_cvt_pk_bf16_f32 v9, v9, v9
	v_mul_f32_e32 v11, 0x3fb8aa3b, v7
	v_sub_f32_e32 v7, v37, v7
	v_mul_f32_e32 v7, 0x3fb8aa3b, v7
	v_exp_f32_e32 v7, v7
	v_exp_f32_e32 v11, v11
	v_lshlrev_b32_e32 v8, 16, v74
	ds_write_b16_d16_hi v6, v9 offset:8976
	v_lshlrev_b32_e32 v9, 16, v73
	v_mul_f32_e32 v7, v7, v8
	v_mul_f32_e32 v9, 0x3e000000, v9
	v_mul_f32_e32 v9, v9, v11
	v_cvt_pk_bf16_f32 v7, v7, v7
	ds_write_b16_d16_hi v6, v7 offset:43296
	v_add_f32_e32 v7, v27, v40
	v_cvt_pk_bf16_f32 v9, v9, v9
	v_mul_f32_e32 v11, 0x3fb8aa3b, v7
	v_sub_f32_e32 v7, v37, v7
	v_mul_f32_e32 v7, 0x3fb8aa3b, v7
	v_exp_f32_e32 v7, v7
	v_exp_f32_e32 v11, v11
	v_lshlrev_b32_e32 v8, 16, v72
	ds_write_b16_d16_hi v6, v9 offset:9504
	v_lshlrev_b32_e32 v9, 16, v71
	v_mul_f32_e32 v7, v7, v8
	v_mul_f32_e32 v9, 0x3e000000, v9
	v_mul_f32_e32 v9, v9, v11
	v_cvt_pk_bf16_f32 v7, v7, v7
	ds_write_b16_d16_hi v6, v7 offset:43824
	v_add_f32_e32 v7, v26, v40
	v_cvt_pk_bf16_f32 v9, v9, v9
	v_mul_f32_e32 v11, 0x3fb8aa3b, v7
	v_sub_f32_e32 v7, v37, v7
	v_mul_f32_e32 v7, 0x3fb8aa3b, v7
	v_exp_f32_e32 v7, v7
	v_exp_f32_e32 v11, v11
	v_lshlrev_b32_e32 v8, 16, v70
	ds_write_b16_d16_hi v6, v9 offset:10032
	v_lshlrev_b32_e32 v9, 16, v69
	v_mul_f32_e32 v7, v7, v8
	v_mul_f32_e32 v9, 0x3e000000, v9
	v_mul_f32_e32 v9, v9, v11
	v_cvt_pk_bf16_f32 v7, v7, v7
	ds_write_b16_d16_hi v6, v7 offset:44352
	v_add_f32_e32 v7, v29, v40
	v_cvt_pk_bf16_f32 v9, v9, v9
	v_mul_f32_e32 v11, 0x3fb8aa3b, v7
	v_sub_f32_e32 v7, v37, v7
	v_mul_f32_e32 v7, 0x3fb8aa3b, v7
	v_exp_f32_e32 v7, v7
	v_exp_f32_e32 v11, v11
	v_lshlrev_b32_e32 v8, 16, v68
	ds_write_b16_d16_hi v6, v9 offset:10560
	v_lshlrev_b32_e32 v9, 16, v67
	v_mul_f32_e32 v7, v7, v8
	v_mul_f32_e32 v9, 0x3e000000, v9
	v_mul_f32_e32 v9, v9, v11
	v_cvt_pk_bf16_f32 v7, v7, v7
	ds_write_b16_d16_hi v6, v7 offset:44880
	v_add_f32_e32 v7, v28, v40
	v_cvt_pk_bf16_f32 v9, v9, v9
	v_mul_f32_e32 v11, 0x3fb8aa3b, v7
	v_sub_f32_e32 v7, v37, v7
	v_mul_f32_e32 v7, 0x3fb8aa3b, v7
	v_exp_f32_e32 v7, v7
	v_exp_f32_e32 v11, v11
	v_lshlrev_b32_e32 v8, 16, v66
	ds_write_b16_d16_hi v6, v9 offset:11088
	v_lshlrev_b32_e32 v9, 16, v65
	v_mul_f32_e32 v7, v7, v8
	v_mul_f32_e32 v9, 0x3e000000, v9
	v_mul_f32_e32 v9, v9, v11
	v_cvt_pk_bf16_f32 v7, v7, v7
	ds_write_b16_d16_hi v6, v7 offset:45408
	v_add_f32_e32 v7, v31, v40
	v_cvt_pk_bf16_f32 v9, v9, v9
	v_mul_f32_e32 v11, 0x3fb8aa3b, v7
	v_sub_f32_e32 v7, v37, v7
	v_mul_f32_e32 v7, 0x3fb8aa3b, v7
	v_exp_f32_e32 v7, v7
	v_exp_f32_e32 v11, v11
	v_lshlrev_b32_e32 v8, 16, v64
	ds_write_b16_d16_hi v6, v9 offset:11616
	v_lshlrev_b32_e32 v9, 16, v63
	v_mul_f32_e32 v7, v7, v8
	v_mul_f32_e32 v9, 0x3e000000, v9
	v_mul_f32_e32 v9, v9, v11
	v_cvt_pk_bf16_f32 v7, v7, v7
	ds_write_b16_d16_hi v6, v7 offset:45936
	v_add_f32_e32 v7, v30, v40
	v_cvt_pk_bf16_f32 v9, v9, v9
	v_mul_f32_e32 v11, 0x3fb8aa3b, v7
	v_sub_f32_e32 v7, v37, v7
	v_mul_f32_e32 v7, 0x3fb8aa3b, v7
	v_exp_f32_e32 v7, v7
	v_exp_f32_e32 v11, v11
	v_lshlrev_b32_e32 v8, 16, v62
	ds_write_b16_d16_hi v6, v9 offset:12144
	v_lshlrev_b32_e32 v9, 16, v61
	v_mul_f32_e32 v7, v7, v8
	v_mul_f32_e32 v9, 0x3e000000, v9
	v_mul_f32_e32 v9, v9, v11
	v_cvt_pk_bf16_f32 v7, v7, v7
	ds_write_b16_d16_hi v6, v7 offset:46464
	v_add_f32_e32 v7, v33, v40
	v_cvt_pk_bf16_f32 v9, v9, v9
	v_mul_f32_e32 v11, 0x3fb8aa3b, v7
	v_sub_f32_e32 v7, v37, v7
	v_mul_f32_e32 v7, 0x3fb8aa3b, v7
	v_exp_f32_e32 v7, v7
	v_exp_f32_e32 v11, v11
	v_lshlrev_b32_e32 v8, 16, v60
	ds_write_b16_d16_hi v6, v9 offset:12672
	v_lshlrev_b32_e32 v9, 16, v59
	v_mul_f32_e32 v7, v7, v8
	v_mul_f32_e32 v9, 0x3e000000, v9
	v_mul_f32_e32 v9, v9, v11
	v_cvt_pk_bf16_f32 v7, v7, v7
	ds_write_b16_d16_hi v6, v7 offset:46992
	v_add_f32_e32 v7, v32, v40
	v_cvt_pk_bf16_f32 v9, v9, v9
	v_mul_f32_e32 v11, 0x3fb8aa3b, v7
	v_sub_f32_e32 v7, v37, v7
	v_mul_f32_e32 v7, 0x3fb8aa3b, v7
	v_exp_f32_e32 v7, v7
	v_exp_f32_e32 v11, v11
	v_lshlrev_b32_e32 v8, 16, v58
	ds_write_b16_d16_hi v6, v9 offset:13200
	v_lshlrev_b32_e32 v9, 16, v57
	v_mul_f32_e32 v7, v7, v8
	v_mul_f32_e32 v9, 0x3e000000, v9
	v_mul_f32_e32 v9, v9, v11
	v_cvt_pk_bf16_f32 v7, v7, v7
	ds_write_b16_d16_hi v6, v7 offset:47520
	v_add_f32_e32 v7, v35, v40
	v_cvt_pk_bf16_f32 v9, v9, v9
	v_mul_f32_e32 v11, 0x3fb8aa3b, v7
	v_sub_f32_e32 v7, v37, v7
	v_mul_f32_e32 v7, 0x3fb8aa3b, v7
	v_exp_f32_e32 v7, v7
	v_exp_f32_e32 v11, v11
	v_lshlrev_b32_e32 v8, 16, v56
	ds_write_b16_d16_hi v6, v9 offset:13728
	v_lshlrev_b32_e32 v9, 16, v55
	v_mul_f32_e32 v7, v7, v8
	v_mul_f32_e32 v9, 0x3e000000, v9
	v_mul_f32_e32 v9, v9, v11
	v_cvt_pk_bf16_f32 v7, v7, v7
	ds_write_b16_d16_hi v6, v7 offset:48048
	v_add_f32_e32 v7, v34, v40
	v_cvt_pk_bf16_f32 v9, v9, v9
	v_mul_f32_e32 v11, 0x3fb8aa3b, v7
	v_sub_f32_e32 v7, v37, v7
	v_mul_f32_e32 v7, 0x3fb8aa3b, v7
	v_exp_f32_e32 v7, v7
	v_exp_f32_e32 v11, v11
	v_lshlrev_b32_e32 v8, 16, v54
	ds_write_b16_d16_hi v6, v9 offset:14256
	v_lshlrev_b32_e32 v9, 16, v53
	v_mul_f32_e32 v7, v7, v8
	v_mul_f32_e32 v9, 0x3e000000, v9
	v_mul_f32_e32 v9, v9, v11
	v_cvt_pk_bf16_f32 v7, v7, v7
	ds_write_b16_d16_hi v6, v7 offset:48576
	v_add_f32_e32 v7, v40, v42
	v_cvt_pk_bf16_f32 v9, v9, v9
	v_mul_f32_e32 v11, 0x3fb8aa3b, v7
	v_sub_f32_e32 v7, v37, v7
	v_mul_f32_e32 v7, 0x3fb8aa3b, v7
	v_exp_f32_e32 v7, v7
	v_exp_f32_e32 v11, v11
	v_lshlrev_b32_e32 v8, 16, v52
	ds_write_b16_d16_hi v6, v9 offset:14784
	v_lshlrev_b32_e32 v9, 16, v50
	v_mul_f32_e32 v7, v7, v8
	v_mul_f32_e32 v9, 0x3e000000, v9
	v_mul_f32_e32 v9, v9, v11
	v_cvt_pk_bf16_f32 v7, v7, v7
	ds_write_b16_d16_hi v6, v7 offset:49104
	v_add_f32_e32 v7, v40, v36
	v_cvt_pk_bf16_f32 v9, v9, v9
	v_mul_f32_e32 v11, 0x3fb8aa3b, v7
	v_sub_f32_e32 v7, v37, v7
	v_mul_f32_e32 v7, 0x3fb8aa3b, v7
	v_exp_f32_e32 v7, v7
	v_exp_f32_e32 v11, v11
	v_lshlrev_b32_e32 v8, 16, v45
	ds_write_b16_d16_hi v6, v9 offset:15312
	v_lshlrev_b32_e32 v9, 16, v48
	v_mul_f32_e32 v7, v7, v8
	v_mul_f32_e32 v9, 0x3e000000, v9
	v_mul_f32_e32 v9, v9, v11
	v_cvt_pk_bf16_f32 v7, v7, v7
	ds_write_b16_d16_hi v6, v7 offset:49632
	v_add_f32_e32 v7, v40, v43
	v_cvt_pk_bf16_f32 v9, v9, v9
	v_mul_f32_e32 v11, 0x3fb8aa3b, v7
	v_sub_f32_e32 v7, v37, v7
	v_mul_f32_e32 v7, 0x3fb8aa3b, v7
	v_exp_f32_e32 v11, v11
	v_exp_f32_e32 v7, v7
	ds_write_b16_d16_hi v6, v9 offset:15840
	v_lshlrev_b32_e32 v9, 16, v41
	v_lshlrev_b32_e32 v8, 16, v39
	v_mul_f32_e32 v9, 0x3e000000, v9
	v_mul_f32_e32 v9, v9, v11
	v_mul_f32_e32 v7, v7, v8
	v_readlane_b32 s0, v255, 1
	v_readlane_b32 s1, v255, 2
	v_cvt_pk_bf16_f32 v9, v9, v9
	v_cvt_pk_bf16_f32 v7, v7, v7
	s_and_b64 s[4:5], s[0:1], vcc
	ds_write_b16_d16_hi v6, v9 offset:16368
	ds_write_b16_d16_hi v6, v7 offset:50160
	s_and_saveexec_b64 s[0:1], s[4:5]
	s_cbranch_execz .LBB0_470
	v_mul_f32_e32 v6, 0x3fb8aa3b, v10
	s_lshl_b64 s[4:5], s[28:29], 10
	v_readlane_b32 s6, v250, 37
	v_exp_f32_e32 v8, v6
	v_readlane_b32 s7, v250, 38
	s_add_u32 s4, s6, s4
	s_addc_u32 s5, s7, s5
	v_mov_b32_e32 v39, v139
	v_lshl_add_u64 v[6:7], v[38:39], 2, s[4:5]
	global_store_dword v[6:7], v8, off

.LBB0_711:
	v_readlane_b32 s50, v253, 48
	v_readlane_b32 s51, v253, 49
	s_movk_i32 s69, 0x4000
	s_movk_i32 s68, 0x2000
	s_mov_b32 s19, 0x8000
	s_mov_b32 s27, 0xc000
	s_mov_b32 s18, 0x14000
	s_movk_i32 s70, 0x6000
	s_barrier
